# v26 + the two loop-invariant LDS read-base adds of six K-loops hoisted out of the loop (into VGPRs freed by the saddr conversion)
# speedup vs baseline: 1.0045x; 1.0004x over previous
.LBB0_133:
	s_ashr_i32 s17, s16, 31
	s_lshl_b64 s[12:13], s[16:17], 21
	s_add_u32 s18, s25, s12
	s_addc_u32 s19, s26, s13
	s_and_b64 s[12:13], s[2:3], exec
	s_cselect_b32 s12, s19, s35
	s_cselect_b32 s13, s18, s34
	s_ashr_i32 s15, s14, 31
	s_lshl_b64 s[20:21], s[14:15], 21
	s_add_u32 s20, s27, s20
	s_addc_u32 s21, s40, s21
	s_and_b64 s[38:39], s[2:3], exec
	s_cselect_b32 s15, s21, s37
	s_cselect_b32 s57, s20, s36
	s_add_u32 s34, s34, 0x100080
	s_addc_u32 s35, s35, 0
	s_add_u32 s58, s36, 0x100
	v_mov_b32_e32 v0, 0
	s_addc_u32 s59, s37, 0
	s_mov_b32 s60, -2
	v_mov_b64_e32 v[0:1], 0
	v_mov_b64_e32 v[2:3], 0
	v_mov_b64_e32 v[4:5], 0
	v_mov_b64_e32 v[6:7], 0
	v_mov_b64_e32 v[8:9], 0
	v_mov_b64_e32 v[10:11], 0
	v_mov_b64_e32 v[12:13], 0
	v_mov_b64_e32 v[14:15], 0
	v_mov_b64_e32 v[16:17], 0
	v_mov_b64_e32 v[18:19], 0
	v_mov_b64_e32 v[20:21], 0
	v_mov_b64_e32 v[22:23], 0
	v_mov_b64_e32 v[24:25], 0
	v_mov_b64_e32 v[26:27], 0
	v_mov_b64_e32 v[28:29], 0
	v_mov_b64_e32 v[30:31], 0
	v_mov_b64_e32 v[32:33], 0
	v_mov_b64_e32 v[34:35], 0
	v_mov_b64_e32 v[36:37], 0
	v_mov_b64_e32 v[38:39], 0
	v_mov_b64_e32 v[40:41], 0
	v_mov_b64_e32 v[42:43], 0
	v_mov_b64_e32 v[44:45], 0
	v_mov_b64_e32 v[46:47], 0
	v_mov_b64_e32 v[48:49], 0
	v_mov_b64_e32 v[50:51], 0
	v_mov_b64_e32 v[52:53], 0
	v_mov_b64_e32 v[54:55], 0
	v_mov_b64_e32 v[56:57], 0
	v_mov_b64_e32 v[58:59], 0
	v_mov_b64_e32 v[60:61], 0
	v_mov_b64_e32 v[62:63], 0
	v_mov_b64_e32 v[64:65], 0
	v_mov_b64_e32 v[66:67], 0
	v_mov_b64_e32 v[68:69], 0
	v_mov_b64_e32 v[70:71], 0
	v_mov_b64_e32 v[72:73], 0
	v_mov_b64_e32 v[74:75], 0
	v_mov_b64_e32 v[76:77], 0
	v_mov_b64_e32 v[78:79], 0
	v_mov_b64_e32 v[80:81], 0
	v_mov_b64_e32 v[82:83], 0
	v_mov_b64_e32 v[84:85], 0
	v_mov_b64_e32 v[86:87], 0
	v_mov_b64_e32 v[88:89], 0
	v_mov_b64_e32 v[90:91], 0
	v_mov_b64_e32 v[92:93], 0
	v_mov_b64_e32 v[94:95], 0
	v_mov_b64_e32 v[96:97], 0
	v_mov_b64_e32 v[98:99], 0
	v_mov_b64_e32 v[100:101], 0
	v_mov_b64_e32 v[102:103], 0
	v_mov_b64_e32 v[104:105], 0
	v_mov_b64_e32 v[106:107], 0
	v_mov_b64_e32 v[108:109], 0
	v_mov_b64_e32 v[110:111], 0
	v_mov_b64_e32 v[112:113], 0
	v_mov_b64_e32 v[114:115], 0
	v_mov_b64_e32 v[116:117], 0
	v_mov_b64_e32 v[118:119], 0
	v_mov_b64_e32 v[120:121], 0
	v_mov_b64_e32 v[122:123], 0
	v_mov_b64_e32 v[124:125], 0
	v_mov_b64_e32 v[126:127], 0
	v_add_u32_e32 v228, 0x18000, v153
	v_add_u32_e32 v229, 0x1c000, v153
.LBB0_134:
	s_add_u32 s0, s34, 0xfff00080
	s_addc_u32 s1, s35, -1
	s_cmp_eq_u32 s60, 60
	s_cselect_b32 s39, s12, s1
	s_cselect_b32 s38, s13, s0
	s_cselect_b32 s37, s15, s59
	s_cselect_b32 s36, s57, s58
	s_add_i32 m0, s29, 0xc000
	ds_read_b128 v[148:151], v156
	global_load_lds_dwordx4 v140, s[34:35]
	s_add_i32 m0, s29, 0xe000
	ds_read_b128 v[160:163], v156 offset:1024
	global_load_lds_dwordx4 v142, s[34:35]
	ds_read_b128 v[164:167], v156 offset:2048
	ds_read_b128 v[168:171], v156 offset:3072
	ds_read_b128 v[172:175], v157
	ds_read_b128 v[176:179], v157 offset:1024
	ds_read_b128 v[180:183], v157 offset:2048
	ds_read_b128 v[184:187], v157 offset:3072
	ds_read_b128 v[188:191], v158
	ds_read_b128 v[192:195], v158 offset:1024
	ds_read_b128 v[196:199], v158 offset:2048
	ds_read_b128 v[200:203], v158 offset:3072
	ds_read_b128 v[208:211], v158 offset:4096
	ds_read_b128 v[212:215], v158 offset:5120
	ds_read_b128 v[216:219], v158 offset:6144
	ds_read_b128 v[220:223], v158 offset:7168
	s_waitcnt vmcnt(8)
	s_waitcnt lgkmcnt(0)
	s_setprio 3
	s_barrier
	v_mfma_f32_16x16x32_bf16 v[124:127], v[148:151], v[188:191], v[124:127]
	v_mfma_f32_16x16x32_bf16 v[120:123], v[164:167], v[188:191], v[120:123]
	v_mfma_f32_16x16x32_bf16 v[108:111], v[148:151], v[196:199], v[108:111]
	v_mfma_f32_16x16x32_bf16 v[104:107], v[164:167], v[196:199], v[104:107]
	v_mfma_f32_16x16x32_bf16 v[92:95], v[148:151], v[208:211], v[92:95]
	v_mfma_f32_16x16x32_bf16 v[88:91], v[164:167], v[208:211], v[88:91]
	v_mfma_f32_16x16x32_bf16 v[76:79], v[148:151], v[216:219], v[76:79]
	v_mfma_f32_16x16x32_bf16 v[72:75], v[164:167], v[216:219], v[72:75]
	v_mfma_f32_16x16x32_bf16 v[124:127], v[160:163], v[192:195], v[124:127]
	v_mfma_f32_16x16x32_bf16 v[120:123], v[168:171], v[192:195], v[120:123]
	v_mfma_f32_16x16x32_bf16 v[108:111], v[160:163], v[200:203], v[108:111]
	v_mfma_f32_16x16x32_bf16 v[104:107], v[168:171], v[200:203], v[104:107]
	v_mfma_f32_16x16x32_bf16 v[92:95], v[160:163], v[212:215], v[92:95]
	v_mfma_f32_16x16x32_bf16 v[88:91], v[168:171], v[212:215], v[88:91]
	v_mfma_f32_16x16x32_bf16 v[76:79], v[160:163], v[220:223], v[76:79]
	v_mfma_f32_16x16x32_bf16 v[72:75], v[168:171], v[220:223], v[72:75]
	s_setprio 0
	s_setprio 3
	v_mfma_f32_16x16x32_bf16 v[116:119], v[172:175], v[188:191], v[116:119]
	v_mfma_f32_16x16x32_bf16 v[112:115], v[180:183], v[188:191], v[112:115]
	v_mfma_f32_16x16x32_bf16 v[100:103], v[172:175], v[196:199], v[100:103]
	v_mfma_f32_16x16x32_bf16 v[96:99], v[180:183], v[196:199], v[96:99]
	v_mfma_f32_16x16x32_bf16 v[84:87], v[172:175], v[208:211], v[84:87]
	v_mfma_f32_16x16x32_bf16 v[80:83], v[180:183], v[208:211], v[80:83]
	v_mfma_f32_16x16x32_bf16 v[68:71], v[172:175], v[216:219], v[68:71]
	v_mfma_f32_16x16x32_bf16 v[64:67], v[180:183], v[216:219], v[64:67]
	v_mfma_f32_16x16x32_bf16 v[116:119], v[176:179], v[192:195], v[116:119]
	v_mfma_f32_16x16x32_bf16 v[112:115], v[184:187], v[192:195], v[112:115]
	v_mfma_f32_16x16x32_bf16 v[100:103], v[176:179], v[200:203], v[100:103]
	v_mfma_f32_16x16x32_bf16 v[96:99], v[184:187], v[200:203], v[96:99]
	v_mfma_f32_16x16x32_bf16 v[84:87], v[176:179], v[212:215], v[84:87]
	v_mfma_f32_16x16x32_bf16 v[80:83], v[184:187], v[212:215], v[80:83]
	v_mfma_f32_16x16x32_bf16 v[68:71], v[176:179], v[220:223], v[68:71]
	v_mfma_f32_16x16x32_bf16 v[64:67], v[184:187], v[220:223], v[64:67]
	s_barrier
	s_setprio 0
	s_add_i32 s0, s51, s41
	s_mov_b32 m0, s0
	ds_read_b128 v[188:191], v158 offset:16384
	global_load_lds_dwordx4 v132, s[36:37]
	s_add_i32 m0, s0, 0x2000
	ds_read_b128 v[192:195], v158 offset:17408
	global_load_lds_dwordx4 v136, s[36:37]
	s_add_u32 s62, s36, 0x100000
	s_addc_u32 s63, s37, 0
	s_add_i32 s0, s52, s41
	s_mov_b32 m0, s0
	ds_read_b128 v[196:199], v158 offset:18432
	global_load_lds_dwordx4 v132, s[62:63]
	s_add_i32 m0, s0, 0x2000
	ds_read_b128 v[200:203], v158 offset:19456
	global_load_lds_dwordx4 v136, s[62:63]
	s_mov_b32 m0, s29
	ds_read_b128 v[208:211], v158 offset:20480
	global_load_lds_dwordx4 v130, s[38:39]
	s_mov_b32 m0, s31
	ds_read_b128 v[212:215], v158 offset:21504
	global_load_lds_dwordx4 v134, s[38:39]
	ds_read_b128 v[216:219], v158 offset:22528
	ds_read_b128 v[220:223], v158 offset:23552
	s_waitcnt vmcnt(8)
	s_waitcnt lgkmcnt(0)
	s_setprio 3
	s_barrier
	v_mfma_f32_16x16x32_bf16 v[60:63], v[148:151], v[188:191], v[60:63]
	v_mfma_f32_16x16x32_bf16 v[56:59], v[164:167], v[188:191], v[56:59]
	v_mfma_f32_16x16x32_bf16 v[44:47], v[148:151], v[196:199], v[44:47]
	v_mfma_f32_16x16x32_bf16 v[40:43], v[164:167], v[196:199], v[40:43]
	v_mfma_f32_16x16x32_bf16 v[28:31], v[148:151], v[208:211], v[28:31]
	v_mfma_f32_16x16x32_bf16 v[24:27], v[164:167], v[208:211], v[24:27]
	v_mfma_f32_16x16x32_bf16 v[12:15], v[148:151], v[216:219], v[12:15]
	v_mfma_f32_16x16x32_bf16 v[8:11], v[164:167], v[216:219], v[8:11]
	v_mfma_f32_16x16x32_bf16 v[60:63], v[160:163], v[192:195], v[60:63]
	v_mfma_f32_16x16x32_bf16 v[56:59], v[168:171], v[192:195], v[56:59]
	v_mfma_f32_16x16x32_bf16 v[44:47], v[160:163], v[200:203], v[44:47]
	v_mfma_f32_16x16x32_bf16 v[40:43], v[168:171], v[200:203], v[40:43]
	v_mfma_f32_16x16x32_bf16 v[28:31], v[160:163], v[212:215], v[28:31]
	v_mfma_f32_16x16x32_bf16 v[24:27], v[168:171], v[212:215], v[24:27]
	v_mfma_f32_16x16x32_bf16 v[12:15], v[160:163], v[220:223], v[12:15]
	v_mfma_f32_16x16x32_bf16 v[8:11], v[168:171], v[220:223], v[8:11]
	s_setprio 0
	s_setprio 3
	v_mfma_f32_16x16x32_bf16 v[52:55], v[172:175], v[188:191], v[52:55]
	v_mfma_f32_16x16x32_bf16 v[48:51], v[180:183], v[188:191], v[48:51]
	v_mfma_f32_16x16x32_bf16 v[36:39], v[172:175], v[196:199], v[36:39]
	v_mfma_f32_16x16x32_bf16 v[32:35], v[180:183], v[196:199], v[32:35]
	v_mfma_f32_16x16x32_bf16 v[20:23], v[172:175], v[208:211], v[20:23]
	v_mfma_f32_16x16x32_bf16 v[16:19], v[180:183], v[208:211], v[16:19]
	v_mfma_f32_16x16x32_bf16 v[4:7], v[172:175], v[216:219], v[4:7]
	v_mfma_f32_16x16x32_bf16 v[0:3], v[180:183], v[216:219], v[0:3]
	v_mfma_f32_16x16x32_bf16 v[52:55], v[176:179], v[192:195], v[52:55]
	v_mfma_f32_16x16x32_bf16 v[48:51], v[184:187], v[192:195], v[48:51]
	v_mfma_f32_16x16x32_bf16 v[36:39], v[176:179], v[200:203], v[36:39]
	v_mfma_f32_16x16x32_bf16 v[32:35], v[184:187], v[200:203], v[32:35]
	v_mfma_f32_16x16x32_bf16 v[20:23], v[176:179], v[212:215], v[20:23]
	v_mfma_f32_16x16x32_bf16 v[16:19], v[184:187], v[212:215], v[16:19]
	v_mfma_f32_16x16x32_bf16 v[4:7], v[176:179], v[220:223], v[4:7]
	v_mfma_f32_16x16x32_bf16 v[0:3], v[184:187], v[220:223], v[0:3]
	s_barrier
	s_setprio 0
	s_add_i32 s0, 0, 0x18000
	s_add_i32 s1, 0, 0x1c000
	ds_read_b128 v[148:151], v228
	ds_read_b128 v[160:163], v228 offset:1024
	ds_read_b128 v[164:167], v228 offset:2048
	ds_read_b128 v[168:171], v228 offset:3072
	ds_read_b128 v[172:175], v229
	ds_read_b128 v[176:179], v229 offset:1024
	ds_read_b128 v[180:183], v229 offset:2048
	ds_read_b128 v[184:187], v229 offset:3072
	s_add_u32 s38, s38, 0x100000
	s_addc_u32 s39, s39, 0
	s_mov_b32 m0, s42
	ds_read_b128 v[188:191], v158 offset:32768
	global_load_lds_dwordx4 v130, s[38:39]
	s_mov_b32 m0, s43
	ds_read_b128 v[192:195], v158 offset:33792
	global_load_lds_dwordx4 v134, s[38:39]
	ds_read_b128 v[196:199], v158 offset:34816
	ds_read_b128 v[200:203], v158 offset:35840
	ds_read_b128 v[208:211], v158 offset:36864
	ds_read_b128 v[212:215], v158 offset:37888
	ds_read_b128 v[216:219], v158 offset:38912
	ds_read_b128 v[220:223], v158 offset:39936
	s_waitcnt vmcnt(8)
	s_waitcnt lgkmcnt(0)
	s_setprio 3
	s_barrier
	v_mfma_f32_16x16x32_bf16 v[124:127], v[148:151], v[188:191], v[124:127]
	v_mfma_f32_16x16x32_bf16 v[120:123], v[164:167], v[188:191], v[120:123]
	v_mfma_f32_16x16x32_bf16 v[108:111], v[148:151], v[196:199], v[108:111]
	v_mfma_f32_16x16x32_bf16 v[104:107], v[164:167], v[196:199], v[104:107]
	v_mfma_f32_16x16x32_bf16 v[92:95], v[148:151], v[208:211], v[92:95]
	v_mfma_f32_16x16x32_bf16 v[88:91], v[164:167], v[208:211], v[88:91]
	v_mfma_f32_16x16x32_bf16 v[76:79], v[148:151], v[216:219], v[76:79]
	v_mfma_f32_16x16x32_bf16 v[72:75], v[164:167], v[216:219], v[72:75]
	v_mfma_f32_16x16x32_bf16 v[124:127], v[160:163], v[192:195], v[124:127]
	v_mfma_f32_16x16x32_bf16 v[120:123], v[168:171], v[192:195], v[120:123]
	v_mfma_f32_16x16x32_bf16 v[108:111], v[160:163], v[200:203], v[108:111]
	v_mfma_f32_16x16x32_bf16 v[104:107], v[168:171], v[200:203], v[104:107]
	v_mfma_f32_16x16x32_bf16 v[92:95], v[160:163], v[212:215], v[92:95]
	v_mfma_f32_16x16x32_bf16 v[88:91], v[168:171], v[212:215], v[88:91]
	v_mfma_f32_16x16x32_bf16 v[76:79], v[160:163], v[220:223], v[76:79]
	v_mfma_f32_16x16x32_bf16 v[72:75], v[168:171], v[220:223], v[72:75]
	s_setprio 0
	s_setprio 3
	v_mfma_f32_16x16x32_bf16 v[116:119], v[172:175], v[188:191], v[116:119]
	v_mfma_f32_16x16x32_bf16 v[112:115], v[180:183], v[188:191], v[112:115]
	v_mfma_f32_16x16x32_bf16 v[100:103], v[172:175], v[196:199], v[100:103]
	v_mfma_f32_16x16x32_bf16 v[96:99], v[180:183], v[196:199], v[96:99]
	v_mfma_f32_16x16x32_bf16 v[84:87], v[172:175], v[208:211], v[84:87]
	v_mfma_f32_16x16x32_bf16 v[80:83], v[180:183], v[208:211], v[80:83]
	v_mfma_f32_16x16x32_bf16 v[68:71], v[172:175], v[216:219], v[68:71]
	v_mfma_f32_16x16x32_bf16 v[64:67], v[180:183], v[216:219], v[64:67]
	v_mfma_f32_16x16x32_bf16 v[116:119], v[176:179], v[192:195], v[116:119]
	v_mfma_f32_16x16x32_bf16 v[112:115], v[184:187], v[192:195], v[112:115]
	v_mfma_f32_16x16x32_bf16 v[100:103], v[176:179], v[200:203], v[100:103]
	v_mfma_f32_16x16x32_bf16 v[96:99], v[184:187], v[200:203], v[96:99]
	v_mfma_f32_16x16x32_bf16 v[84:87], v[176:179], v[212:215], v[84:87]
	v_mfma_f32_16x16x32_bf16 v[80:83], v[184:187], v[212:215], v[80:83]
	v_mfma_f32_16x16x32_bf16 v[68:71], v[176:179], v[220:223], v[68:71]
	v_mfma_f32_16x16x32_bf16 v[64:67], v[184:187], v[220:223], v[64:67]
	s_barrier
	s_setprio 0
	s_add_i32 s0, s0, s41
	s_add_u32 s100, s36, 0x80
	s_addc_u32 s101, s37, 0
	s_mov_b32 m0, s0
	ds_read_b128 v[188:191], v158 offset:49152
	global_load_lds_dwordx4 v132, s[100:101]
	s_add_i32 m0, s0, 0x2000
	ds_read_b128 v[192:195], v158 offset:50176
	global_load_lds_dwordx4 v136, s[100:101]
	s_add_u32 s36, s36, 0x100080
	s_addc_u32 s37, s37, 0
	s_add_i32 s0, s1, s41
	s_mov_b32 m0, s0
	ds_read_b128 v[196:199], v158 offset:51200
	global_load_lds_dwordx4 v132, s[36:37]
	s_add_i32 m0, s0, 0x2000
	ds_read_b128 v[200:203], v158 offset:52224
	global_load_lds_dwordx4 v136, s[36:37]
	s_add_u32 s100, s38, 0xfff00080
	s_addc_u32 s101, s39, -1
	s_mov_b32 m0, s46
	ds_read_b128 v[208:211], v158 offset:53248
	global_load_lds_dwordx4 v130, s[100:101]
	s_mov_b32 m0, s47
	ds_read_b128 v[212:215], v158 offset:54272
	global_load_lds_dwordx4 v134, s[100:101]
	ds_read_b128 v[216:219], v158 offset:55296
	ds_read_b128 v[220:223], v158 offset:56320
	s_waitcnt vmcnt(8)
	s_waitcnt lgkmcnt(0)
	s_setprio 3
	s_barrier
	v_mfma_f32_16x16x32_bf16 v[60:63], v[148:151], v[188:191], v[60:63]
	v_mfma_f32_16x16x32_bf16 v[56:59], v[164:167], v[188:191], v[56:59]
	v_mfma_f32_16x16x32_bf16 v[44:47], v[148:151], v[196:199], v[44:47]
	v_mfma_f32_16x16x32_bf16 v[40:43], v[164:167], v[196:199], v[40:43]
	v_mfma_f32_16x16x32_bf16 v[28:31], v[148:151], v[208:211], v[28:31]
	v_mfma_f32_16x16x32_bf16 v[24:27], v[164:167], v[208:211], v[24:27]
	v_mfma_f32_16x16x32_bf16 v[12:15], v[148:151], v[216:219], v[12:15]
	v_mfma_f32_16x16x32_bf16 v[8:11], v[164:167], v[216:219], v[8:11]
	v_mfma_f32_16x16x32_bf16 v[60:63], v[160:163], v[192:195], v[60:63]
	v_mfma_f32_16x16x32_bf16 v[56:59], v[168:171], v[192:195], v[56:59]
	v_mfma_f32_16x16x32_bf16 v[44:47], v[160:163], v[200:203], v[44:47]
	v_mfma_f32_16x16x32_bf16 v[40:43], v[168:171], v[200:203], v[40:43]
	v_mfma_f32_16x16x32_bf16 v[28:31], v[160:163], v[212:215], v[28:31]
	v_mfma_f32_16x16x32_bf16 v[24:27], v[168:171], v[212:215], v[24:27]
	v_mfma_f32_16x16x32_bf16 v[12:15], v[160:163], v[220:223], v[12:15]
	v_mfma_f32_16x16x32_bf16 v[8:11], v[168:171], v[220:223], v[8:11]
	s_setprio 0
	s_setprio 3
	v_mfma_f32_16x16x32_bf16 v[52:55], v[172:175], v[188:191], v[52:55]
	v_mfma_f32_16x16x32_bf16 v[48:51], v[180:183], v[188:191], v[48:51]
	v_mfma_f32_16x16x32_bf16 v[36:39], v[172:175], v[196:199], v[36:39]
	v_mfma_f32_16x16x32_bf16 v[32:35], v[180:183], v[196:199], v[32:35]
	v_mfma_f32_16x16x32_bf16 v[20:23], v[172:175], v[208:211], v[20:23]
	v_mfma_f32_16x16x32_bf16 v[16:19], v[180:183], v[208:211], v[16:19]
	v_mfma_f32_16x16x32_bf16 v[4:7], v[172:175], v[216:219], v[4:7]
	v_mfma_f32_16x16x32_bf16 v[0:3], v[180:183], v[216:219], v[0:3]
	v_mfma_f32_16x16x32_bf16 v[52:55], v[176:179], v[192:195], v[52:55]
	v_mfma_f32_16x16x32_bf16 v[48:51], v[184:187], v[192:195], v[48:51]
	v_mfma_f32_16x16x32_bf16 v[36:39], v[176:179], v[200:203], v[36:39]
	v_mfma_f32_16x16x32_bf16 v[32:35], v[184:187], v[200:203], v[32:35]
	v_mfma_f32_16x16x32_bf16 v[20:23], v[176:179], v[212:215], v[20:23]
	v_mfma_f32_16x16x32_bf16 v[16:19], v[184:187], v[212:215], v[16:19]
	v_mfma_f32_16x16x32_bf16 v[4:7], v[176:179], v[220:223], v[4:7]
	v_mfma_f32_16x16x32_bf16 v[0:3], v[184:187], v[220:223], v[0:3]
	s_barrier
	s_setprio 0
	s_add_u32 s34, s34, 0x100
	s_addc_u32 s35, s35, 0
	s_add_i32 s60, s60, 2
	s_add_u32 s58, s58, 0x100
	s_addc_u32 s59, s59, 0
	s_cmp_gt_u32 s60, 61
	s_cbranch_scc0 .LBB0_134
	s_and_b64 vcc, exec, s[10:11]
	s_cbranch_vccz .LBB0_137
	s_barrier

.LBB0_676:
	s_ashr_i32 s17, s16, 31
	s_lshl_b64 s[0:1], s[16:17], 21
	s_add_u32 s18, s25, s0
	s_addc_u32 s19, s26, s1
	s_and_b64 s[0:1], s[2:3], exec
	s_cselect_b32 s56, s19, s37
	s_cselect_b32 s57, s18, s36
	s_ashr_i32 s15, s14, 31
	s_lshl_b64 s[0:1], s[14:15], 21
	s_add_u32 s20, s27, s0
	s_addc_u32 s21, s42, s1
	s_and_b64 s[0:1], s[2:3], exec
	s_cselect_b32 s15, s21, s39
	s_cselect_b32 s58, s20, s38
	s_add_u32 s36, s36, 0x100080
	s_addc_u32 s37, s37, 0
	s_add_u32 s59, s38, 0x100
	v_mov_b32_e32 v0, 0
	s_addc_u32 s60, s39, 0
	s_mov_b32 s61, -2
	v_mov_b64_e32 v[0:1], 0
	v_mov_b64_e32 v[2:3], 0
	v_mov_b64_e32 v[4:5], 0
	v_mov_b64_e32 v[6:7], 0
	v_mov_b64_e32 v[8:9], 0
	v_mov_b64_e32 v[10:11], 0
	v_mov_b64_e32 v[12:13], 0
	v_mov_b64_e32 v[14:15], 0
	v_mov_b64_e32 v[16:17], 0
	v_mov_b64_e32 v[18:19], 0
	v_mov_b64_e32 v[20:21], 0
	v_mov_b64_e32 v[22:23], 0
	v_mov_b64_e32 v[24:25], 0
	v_mov_b64_e32 v[26:27], 0
	v_mov_b64_e32 v[28:29], 0
	v_mov_b64_e32 v[30:31], 0
	v_mov_b64_e32 v[32:33], 0
	v_mov_b64_e32 v[34:35], 0
	v_mov_b64_e32 v[36:37], 0
	v_mov_b64_e32 v[38:39], 0
	v_mov_b64_e32 v[40:41], 0
	v_mov_b64_e32 v[42:43], 0
	v_mov_b64_e32 v[44:45], 0
	v_mov_b64_e32 v[46:47], 0
	v_mov_b64_e32 v[48:49], 0
	v_mov_b64_e32 v[50:51], 0
	v_mov_b64_e32 v[52:53], 0
	v_mov_b64_e32 v[54:55], 0
	v_mov_b64_e32 v[56:57], 0
	v_mov_b64_e32 v[58:59], 0
	v_mov_b64_e32 v[60:61], 0
	v_mov_b64_e32 v[62:63], 0
	v_mov_b64_e32 v[64:65], 0
	v_mov_b64_e32 v[66:67], 0
	v_mov_b64_e32 v[68:69], 0
	v_mov_b64_e32 v[70:71], 0
	v_mov_b64_e32 v[72:73], 0
	v_mov_b64_e32 v[74:75], 0
	v_mov_b64_e32 v[76:77], 0
	v_mov_b64_e32 v[78:79], 0
	v_mov_b64_e32 v[80:81], 0
	v_mov_b64_e32 v[82:83], 0
	v_mov_b64_e32 v[84:85], 0
	v_mov_b64_e32 v[86:87], 0
	v_mov_b64_e32 v[88:89], 0
	v_mov_b64_e32 v[90:91], 0
	v_mov_b64_e32 v[92:93], 0
	v_mov_b64_e32 v[94:95], 0
	v_mov_b64_e32 v[96:97], 0
	v_mov_b64_e32 v[98:99], 0
	v_mov_b64_e32 v[100:101], 0
	v_mov_b64_e32 v[102:103], 0
	v_mov_b64_e32 v[104:105], 0
	v_mov_b64_e32 v[106:107], 0
	v_mov_b64_e32 v[108:109], 0
	v_mov_b64_e32 v[110:111], 0
	v_mov_b64_e32 v[112:113], 0
	v_mov_b64_e32 v[114:115], 0
	v_mov_b64_e32 v[116:117], 0
	v_mov_b64_e32 v[118:119], 0
	v_mov_b64_e32 v[120:121], 0
	v_mov_b64_e32 v[122:123], 0
	v_mov_b64_e32 v[124:125], 0
	v_mov_b64_e32 v[126:127], 0
	v_add_u32_e32 v226, 0x18000, v149
	v_add_u32_e32 v227, 0x1c000, v149
.LBB0_677:
	ds_read_b128 v[156:159], v152
	ds_read_b128 v[160:163], v152 offset:1024
	ds_read_b128 v[164:167], v152 offset:2048
	ds_read_b128 v[168:171], v152 offset:3072
	ds_read_b128 v[172:175], v153
	ds_read_b128 v[176:179], v153 offset:1024
	ds_read_b128 v[180:183], v153 offset:2048
	ds_read_b128 v[184:187], v153 offset:3072
	s_add_u32 s0, s36, 0xfff00080
	s_addc_u32 s1, s37, -1
	s_cmp_eq_u32 s61, 60
	s_cselect_b32 s41, s56, s1
	s_cselect_b32 s40, s57, s0
	s_cselect_b32 s39, s15, s60
	s_cselect_b32 s38, s58, s59
	s_add_i32 m0, s31, 0xc000
	ds_read_b128 v[188:191], v154
	ds_read_b128 v[192:195], v154 offset:1024
	ds_read_b128 v[196:199], v154 offset:2048
	ds_read_b128 v[200:203], v154 offset:3072
	ds_read_b128 v[204:207], v154 offset:4096
	ds_read_b128 v[208:211], v154 offset:5120
	ds_read_b128 v[212:215], v154 offset:6144
	global_load_lds_dwordx4 v138, s[36:37]
	s_add_i32 m0, s31, 0xe000
	ds_read_b128 v[216:219], v154 offset:7168
	global_load_lds_dwordx4 v140, s[36:37]
	s_waitcnt vmcnt(8)
	s_waitcnt lgkmcnt(0)
	s_setprio 3
	s_barrier
	v_mfma_f32_16x16x32_bf16 v[124:127], v[156:159], v[188:191], v[124:127]
	v_mfma_f32_16x16x32_bf16 v[120:123], v[164:167], v[188:191], v[120:123]
	v_mfma_f32_16x16x32_bf16 v[108:111], v[156:159], v[196:199], v[108:111]
	v_mfma_f32_16x16x32_bf16 v[104:107], v[164:167], v[196:199], v[104:107]
	v_mfma_f32_16x16x32_bf16 v[92:95], v[156:159], v[204:207], v[92:95]
	v_mfma_f32_16x16x32_bf16 v[88:91], v[164:167], v[204:207], v[88:91]
	v_mfma_f32_16x16x32_bf16 v[76:79], v[156:159], v[212:215], v[76:79]
	v_mfma_f32_16x16x32_bf16 v[72:75], v[164:167], v[212:215], v[72:75]
	v_mfma_f32_16x16x32_bf16 v[124:127], v[160:163], v[192:195], v[124:127]
	v_mfma_f32_16x16x32_bf16 v[120:123], v[168:171], v[192:195], v[120:123]
	v_mfma_f32_16x16x32_bf16 v[108:111], v[160:163], v[200:203], v[108:111]
	v_mfma_f32_16x16x32_bf16 v[104:107], v[168:171], v[200:203], v[104:107]
	v_mfma_f32_16x16x32_bf16 v[92:95], v[160:163], v[208:211], v[92:95]
	v_mfma_f32_16x16x32_bf16 v[88:91], v[168:171], v[208:211], v[88:91]
	v_mfma_f32_16x16x32_bf16 v[76:79], v[160:163], v[216:219], v[76:79]
	v_mfma_f32_16x16x32_bf16 v[72:75], v[168:171], v[216:219], v[72:75]
	s_setprio 0
	s_setprio 3
	v_mfma_f32_16x16x32_bf16 v[116:119], v[172:175], v[188:191], v[116:119]
	v_mfma_f32_16x16x32_bf16 v[112:115], v[180:183], v[188:191], v[112:115]
	v_mfma_f32_16x16x32_bf16 v[100:103], v[172:175], v[196:199], v[100:103]
	v_mfma_f32_16x16x32_bf16 v[96:99], v[180:183], v[196:199], v[96:99]
	v_mfma_f32_16x16x32_bf16 v[84:87], v[172:175], v[204:207], v[84:87]
	v_mfma_f32_16x16x32_bf16 v[80:83], v[180:183], v[204:207], v[80:83]
	v_mfma_f32_16x16x32_bf16 v[68:71], v[172:175], v[212:215], v[68:71]
	v_mfma_f32_16x16x32_bf16 v[64:67], v[180:183], v[212:215], v[64:67]
	v_mfma_f32_16x16x32_bf16 v[116:119], v[176:179], v[192:195], v[116:119]
	v_mfma_f32_16x16x32_bf16 v[112:115], v[184:187], v[192:195], v[112:115]
	v_mfma_f32_16x16x32_bf16 v[100:103], v[176:179], v[200:203], v[100:103]
	v_mfma_f32_16x16x32_bf16 v[96:99], v[184:187], v[200:203], v[96:99]
	v_mfma_f32_16x16x32_bf16 v[84:87], v[176:179], v[208:211], v[84:87]
	v_mfma_f32_16x16x32_bf16 v[80:83], v[184:187], v[208:211], v[80:83]
	v_mfma_f32_16x16x32_bf16 v[68:71], v[176:179], v[216:219], v[68:71]
	v_mfma_f32_16x16x32_bf16 v[64:67], v[184:187], v[216:219], v[64:67]
	s_barrier
	s_setprio 0
	s_add_i32 s0, s51, s43
	s_mov_b32 m0, s0
	ds_read_b128 v[188:191], v154 offset:16384
	ds_read_b128 v[192:195], v154 offset:17408
	ds_read_b128 v[196:199], v154 offset:18432
	ds_read_b128 v[200:203], v154 offset:19456
	ds_read_b128 v[204:207], v154 offset:20480
	global_load_lds_dwordx4 v130, s[38:39]
	s_add_i32 m0, s0, 0x2000
	s_add_u32 s0, s38, 0x100000
	s_addc_u32 s1, s39, 0
	s_add_i32 s62, s52, s43
	global_load_lds_dwordx4 v134, s[38:39]
	s_mov_b32 m0, s62
	s_nop 0
	global_load_lds_dwordx4 v130, s[0:1]
	s_add_i32 m0, s62, 0x2000
	ds_read_b128 v[216:219], v154 offset:23552
	global_load_lds_dwordx4 v134, s[0:1]
	s_mov_b32 m0, s31
	ds_read_b128 v[212:215], v154 offset:22528
	global_load_lds_dwordx4 v128, s[40:41]
	s_mov_b32 m0, s35
	ds_read_b128 v[208:211], v154 offset:21504
	global_load_lds_dwordx4 v132, s[40:41]
	s_waitcnt vmcnt(8)
	s_waitcnt lgkmcnt(0)
	s_setprio 3
	s_barrier
	v_mfma_f32_16x16x32_bf16 v[60:63], v[156:159], v[188:191], v[60:63]
	v_mfma_f32_16x16x32_bf16 v[56:59], v[164:167], v[188:191], v[56:59]
	v_mfma_f32_16x16x32_bf16 v[44:47], v[156:159], v[196:199], v[44:47]
	v_mfma_f32_16x16x32_bf16 v[40:43], v[164:167], v[196:199], v[40:43]
	v_mfma_f32_16x16x32_bf16 v[28:31], v[156:159], v[204:207], v[28:31]
	v_mfma_f32_16x16x32_bf16 v[24:27], v[164:167], v[204:207], v[24:27]
	v_mfma_f32_16x16x32_bf16 v[12:15], v[156:159], v[212:215], v[12:15]
	v_mfma_f32_16x16x32_bf16 v[8:11], v[164:167], v[212:215], v[8:11]
	v_mfma_f32_16x16x32_bf16 v[60:63], v[160:163], v[192:195], v[60:63]
	v_mfma_f32_16x16x32_bf16 v[56:59], v[168:171], v[192:195], v[56:59]
	v_mfma_f32_16x16x32_bf16 v[44:47], v[160:163], v[200:203], v[44:47]
	v_mfma_f32_16x16x32_bf16 v[40:43], v[168:171], v[200:203], v[40:43]
	v_mfma_f32_16x16x32_bf16 v[28:31], v[160:163], v[208:211], v[28:31]
	v_mfma_f32_16x16x32_bf16 v[24:27], v[168:171], v[208:211], v[24:27]
	v_mfma_f32_16x16x32_bf16 v[12:15], v[160:163], v[216:219], v[12:15]
	v_mfma_f32_16x16x32_bf16 v[8:11], v[168:171], v[216:219], v[8:11]
	s_setprio 0
	s_setprio 3
	v_mfma_f32_16x16x32_bf16 v[52:55], v[172:175], v[188:191], v[52:55]
	v_mfma_f32_16x16x32_bf16 v[48:51], v[180:183], v[188:191], v[48:51]
	v_mfma_f32_16x16x32_bf16 v[36:39], v[172:175], v[196:199], v[36:39]
	v_mfma_f32_16x16x32_bf16 v[32:35], v[180:183], v[196:199], v[32:35]
	v_mfma_f32_16x16x32_bf16 v[20:23], v[172:175], v[204:207], v[20:23]
	v_mfma_f32_16x16x32_bf16 v[16:19], v[180:183], v[204:207], v[16:19]
	v_mfma_f32_16x16x32_bf16 v[4:7], v[172:175], v[212:215], v[4:7]
	v_mfma_f32_16x16x32_bf16 v[0:3], v[180:183], v[212:215], v[0:3]
	v_mfma_f32_16x16x32_bf16 v[52:55], v[176:179], v[192:195], v[52:55]
	v_mfma_f32_16x16x32_bf16 v[48:51], v[184:187], v[192:195], v[48:51]
	v_mfma_f32_16x16x32_bf16 v[36:39], v[176:179], v[200:203], v[36:39]
	v_mfma_f32_16x16x32_bf16 v[32:35], v[184:187], v[200:203], v[32:35]
	v_mfma_f32_16x16x32_bf16 v[20:23], v[176:179], v[208:211], v[20:23]
	v_mfma_f32_16x16x32_bf16 v[16:19], v[184:187], v[208:211], v[16:19]
	v_mfma_f32_16x16x32_bf16 v[4:7], v[176:179], v[216:219], v[4:7]
	v_mfma_f32_16x16x32_bf16 v[0:3], v[184:187], v[216:219], v[0:3]
	s_barrier
	s_setprio 0
	s_add_i32 s62, 0, 0x18000
	s_add_i32 s63, 0, 0x1c000
	ds_read_b128 v[156:159], v226
	ds_read_b128 v[160:163], v226 offset:1024
	ds_read_b128 v[164:167], v226 offset:2048
	ds_read_b128 v[168:171], v226 offset:3072
	ds_read_b128 v[172:175], v227
	ds_read_b128 v[176:179], v227 offset:1024
	ds_read_b128 v[180:183], v227 offset:2048
	ds_read_b128 v[184:187], v227 offset:3072
	s_add_u32 s0, s40, 0x100000
	s_addc_u32 s1, s41, 0
	s_mov_b32 m0, s44
	ds_read_b128 v[188:191], v154 offset:32768
	ds_read_b128 v[192:195], v154 offset:33792
	ds_read_b128 v[196:199], v154 offset:34816
	ds_read_b128 v[200:203], v154 offset:35840
	ds_read_b128 v[204:207], v154 offset:36864
	ds_read_b128 v[208:211], v154 offset:37888
	ds_read_b128 v[212:215], v154 offset:38912
	global_load_lds_dwordx4 v128, s[0:1]
	s_mov_b32 m0, s45
	ds_read_b128 v[216:219], v154 offset:39936
	global_load_lds_dwordx4 v132, s[0:1]
	s_waitcnt vmcnt(8)
	s_waitcnt lgkmcnt(0)
	s_setprio 3
	s_barrier
	v_mfma_f32_16x16x32_bf16 v[124:127], v[156:159], v[188:191], v[124:127]
	v_mfma_f32_16x16x32_bf16 v[120:123], v[164:167], v[188:191], v[120:123]
	v_mfma_f32_16x16x32_bf16 v[108:111], v[156:159], v[196:199], v[108:111]
	v_mfma_f32_16x16x32_bf16 v[104:107], v[164:167], v[196:199], v[104:107]
	v_mfma_f32_16x16x32_bf16 v[92:95], v[156:159], v[204:207], v[92:95]
	v_mfma_f32_16x16x32_bf16 v[88:91], v[164:167], v[204:207], v[88:91]
	v_mfma_f32_16x16x32_bf16 v[76:79], v[156:159], v[212:215], v[76:79]
	v_mfma_f32_16x16x32_bf16 v[72:75], v[164:167], v[212:215], v[72:75]
	v_mfma_f32_16x16x32_bf16 v[124:127], v[160:163], v[192:195], v[124:127]
	v_mfma_f32_16x16x32_bf16 v[120:123], v[168:171], v[192:195], v[120:123]
	v_mfma_f32_16x16x32_bf16 v[108:111], v[160:163], v[200:203], v[108:111]
	v_mfma_f32_16x16x32_bf16 v[104:107], v[168:171], v[200:203], v[104:107]
	v_mfma_f32_16x16x32_bf16 v[92:95], v[160:163], v[208:211], v[92:95]
	v_mfma_f32_16x16x32_bf16 v[88:91], v[168:171], v[208:211], v[88:91]
	v_mfma_f32_16x16x32_bf16 v[76:79], v[160:163], v[216:219], v[76:79]
	v_mfma_f32_16x16x32_bf16 v[72:75], v[168:171], v[216:219], v[72:75]
	s_setprio 0
	s_setprio 3
	v_mfma_f32_16x16x32_bf16 v[116:119], v[172:175], v[188:191], v[116:119]
	v_mfma_f32_16x16x32_bf16 v[112:115], v[180:183], v[188:191], v[112:115]
	v_mfma_f32_16x16x32_bf16 v[100:103], v[172:175], v[196:199], v[100:103]
	v_mfma_f32_16x16x32_bf16 v[96:99], v[180:183], v[196:199], v[96:99]
	v_mfma_f32_16x16x32_bf16 v[84:87], v[172:175], v[204:207], v[84:87]
	v_mfma_f32_16x16x32_bf16 v[80:83], v[180:183], v[204:207], v[80:83]
	v_mfma_f32_16x16x32_bf16 v[68:71], v[172:175], v[212:215], v[68:71]
	v_mfma_f32_16x16x32_bf16 v[64:67], v[180:183], v[212:215], v[64:67]
	v_mfma_f32_16x16x32_bf16 v[116:119], v[176:179], v[192:195], v[116:119]
	v_mfma_f32_16x16x32_bf16 v[112:115], v[184:187], v[192:195], v[112:115]
	v_mfma_f32_16x16x32_bf16 v[100:103], v[176:179], v[200:203], v[100:103]
	v_mfma_f32_16x16x32_bf16 v[96:99], v[184:187], v[200:203], v[96:99]
	v_mfma_f32_16x16x32_bf16 v[84:87], v[176:179], v[208:211], v[84:87]
	v_mfma_f32_16x16x32_bf16 v[80:83], v[184:187], v[208:211], v[80:83]
	v_mfma_f32_16x16x32_bf16 v[68:71], v[176:179], v[216:219], v[68:71]
	v_mfma_f32_16x16x32_bf16 v[64:67], v[184:187], v[216:219], v[64:67]
	s_barrier
	s_setprio 0
	s_add_i32 s0, s62, s43
	s_add_u32 s100, s38, 0x80
	s_addc_u32 s101, s39, 0
	s_mov_b32 m0, s0
	ds_read_b128 v[188:191], v154 offset:49152
	ds_read_b128 v[192:195], v154 offset:50176
	ds_read_b128 v[196:199], v154 offset:51200
	ds_read_b128 v[200:203], v154 offset:52224
	global_load_lds_dwordx4 v130, s[100:101]
	s_add_i32 m0, s0, 0x2000
	s_add_u32 s100, s38, 0x80
	s_addc_u32 s101, s39, 0
	s_add_u32 s0, s38, 0x100080
	s_addc_u32 s1, s39, 0
	s_add_i32 s38, s63, s43
	global_load_lds_dwordx4 v134, s[100:101]
	s_mov_b32 m0, s38
	ds_read_b128 v[216:219], v154 offset:56320
	global_load_lds_dwordx4 v130, s[0:1]
	s_add_i32 m0, s38, 0x2000
	ds_read_b128 v[212:215], v154 offset:55296
	global_load_lds_dwordx4 v134, s[0:1]
	s_add_u32 s100, s40, 0x80
	s_addc_u32 s101, s41, 0
	s_mov_b32 m0, s46
	ds_read_b128 v[208:211], v154 offset:54272
	global_load_lds_dwordx4 v128, s[100:101]
	s_add_u32 s100, s40, 0x80
	s_addc_u32 s101, s41, 0
	s_mov_b32 m0, s47
	ds_read_b128 v[204:207], v154 offset:53248
	global_load_lds_dwordx4 v132, s[100:101]
	s_waitcnt vmcnt(8)
	s_waitcnt lgkmcnt(0)
	s_setprio 3
	s_barrier
	v_mfma_f32_16x16x32_bf16 v[60:63], v[156:159], v[188:191], v[60:63]
	v_mfma_f32_16x16x32_bf16 v[56:59], v[164:167], v[188:191], v[56:59]
	v_mfma_f32_16x16x32_bf16 v[44:47], v[156:159], v[196:199], v[44:47]
	v_mfma_f32_16x16x32_bf16 v[40:43], v[164:167], v[196:199], v[40:43]
	v_mfma_f32_16x16x32_bf16 v[28:31], v[156:159], v[204:207], v[28:31]
	v_mfma_f32_16x16x32_bf16 v[24:27], v[164:167], v[204:207], v[24:27]
	v_mfma_f32_16x16x32_bf16 v[12:15], v[156:159], v[212:215], v[12:15]
	v_mfma_f32_16x16x32_bf16 v[8:11], v[164:167], v[212:215], v[8:11]
	v_mfma_f32_16x16x32_bf16 v[60:63], v[160:163], v[192:195], v[60:63]
	v_mfma_f32_16x16x32_bf16 v[56:59], v[168:171], v[192:195], v[56:59]
	v_mfma_f32_16x16x32_bf16 v[44:47], v[160:163], v[200:203], v[44:47]
	v_mfma_f32_16x16x32_bf16 v[40:43], v[168:171], v[200:203], v[40:43]
	v_mfma_f32_16x16x32_bf16 v[28:31], v[160:163], v[208:211], v[28:31]
	v_mfma_f32_16x16x32_bf16 v[24:27], v[168:171], v[208:211], v[24:27]
	v_mfma_f32_16x16x32_bf16 v[12:15], v[160:163], v[216:219], v[12:15]
	v_mfma_f32_16x16x32_bf16 v[8:11], v[168:171], v[216:219], v[8:11]
	s_setprio 0
	s_setprio 3
	v_mfma_f32_16x16x32_bf16 v[52:55], v[172:175], v[188:191], v[52:55]
	v_mfma_f32_16x16x32_bf16 v[48:51], v[180:183], v[188:191], v[48:51]
	v_mfma_f32_16x16x32_bf16 v[36:39], v[172:175], v[196:199], v[36:39]
	v_mfma_f32_16x16x32_bf16 v[32:35], v[180:183], v[196:199], v[32:35]
	v_mfma_f32_16x16x32_bf16 v[20:23], v[172:175], v[204:207], v[20:23]
	v_mfma_f32_16x16x32_bf16 v[16:19], v[180:183], v[204:207], v[16:19]
	v_mfma_f32_16x16x32_bf16 v[4:7], v[172:175], v[212:215], v[4:7]
	v_mfma_f32_16x16x32_bf16 v[0:3], v[180:183], v[212:215], v[0:3]
	v_mfma_f32_16x16x32_bf16 v[52:55], v[176:179], v[192:195], v[52:55]
	v_mfma_f32_16x16x32_bf16 v[48:51], v[184:187], v[192:195], v[48:51]
	v_mfma_f32_16x16x32_bf16 v[36:39], v[176:179], v[200:203], v[36:39]
	v_mfma_f32_16x16x32_bf16 v[32:35], v[184:187], v[200:203], v[32:35]
	v_mfma_f32_16x16x32_bf16 v[20:23], v[176:179], v[208:211], v[20:23]
	v_mfma_f32_16x16x32_bf16 v[16:19], v[184:187], v[208:211], v[16:19]
	v_mfma_f32_16x16x32_bf16 v[4:7], v[176:179], v[216:219], v[4:7]
	v_mfma_f32_16x16x32_bf16 v[0:3], v[184:187], v[216:219], v[0:3]
	s_barrier
	s_setprio 0
	s_add_u32 s36, s36, 0x100
	s_addc_u32 s37, s37, 0
	s_add_i32 s61, s61, 2
	s_add_u32 s59, s59, 0x100
	s_addc_u32 s60, s60, 0
	s_cmp_gt_u32 s61, 61
	s_cbranch_scc0 .LBB0_677
	s_and_b64 vcc, exec, s[12:13]
	s_cbranch_vccz .LBB0_680
	s_barrier

.LBB0_704:
	s_ashr_i32 s35, s34, 31
	s_lshl_b64 s[0:1], s[34:35], 20
	s_add_u32 s36, s25, s0
	s_addc_u32 s37, s26, s1
	s_and_b64 s[0:1], s[2:3], exec
	s_cselect_b32 s60, s37, s45
	s_cselect_b32 s66, s36, s44
	s_ashr_i32 s31, s30, 31
	s_lshl_b64 s[0:1], s[30:31], 20
	s_add_u32 s38, s27, s0
	s_addc_u32 s39, s50, s1
	s_and_b64 s[0:1], s[2:3], exec
	s_cselect_b32 s31, s39, s47
	s_cselect_b32 s67, s38, s46
	s_add_u32 s44, s44, 0x80080
	s_addc_u32 s45, s45, 0
	s_add_u32 s68, s46, 0x100
	v_mov_b32_e32 v32, 0
	s_addc_u32 s69, s47, 0
	s_mov_b32 s70, -2
	v_mov_b64_e32 v[32:33], 0
	v_mov_b64_e32 v[34:35], 0
	v_mov_b64_e32 v[36:37], 0
	v_mov_b64_e32 v[38:39], 0
	v_mov_b64_e32 v[40:41], 0
	v_mov_b64_e32 v[42:43], 0
	v_mov_b64_e32 v[44:45], 0
	v_mov_b64_e32 v[46:47], 0
	v_mov_b64_e32 v[48:49], 0
	v_mov_b64_e32 v[50:51], 0
	v_mov_b64_e32 v[52:53], 0
	v_mov_b64_e32 v[54:55], 0
	v_mov_b64_e32 v[56:57], 0
	v_mov_b64_e32 v[58:59], 0
	v_mov_b64_e32 v[60:61], 0
	v_mov_b64_e32 v[62:63], 0
	v_mov_b64_e32 v[64:65], 0
	v_mov_b64_e32 v[66:67], 0
	v_mov_b64_e32 v[68:69], 0
	v_mov_b64_e32 v[70:71], 0
	v_mov_b64_e32 v[72:73], 0
	v_mov_b64_e32 v[74:75], 0
	v_mov_b64_e32 v[76:77], 0
	v_mov_b64_e32 v[78:79], 0
	v_mov_b64_e32 v[80:81], 0
	v_mov_b64_e32 v[82:83], 0
	v_mov_b64_e32 v[84:85], 0
	v_mov_b64_e32 v[86:87], 0
	v_mov_b64_e32 v[88:89], 0
	v_mov_b64_e32 v[90:91], 0
	v_mov_b64_e32 v[92:93], 0
	v_mov_b64_e32 v[94:95], 0
	v_mov_b64_e32 v[96:97], 0
	v_mov_b64_e32 v[98:99], 0
	v_mov_b64_e32 v[100:101], 0
	v_mov_b64_e32 v[102:103], 0
	v_mov_b64_e32 v[104:105], 0
	v_mov_b64_e32 v[106:107], 0
	v_mov_b64_e32 v[108:109], 0
	v_mov_b64_e32 v[110:111], 0
	v_mov_b64_e32 v[112:113], 0
	v_mov_b64_e32 v[114:115], 0
	v_mov_b64_e32 v[116:117], 0
	v_mov_b64_e32 v[118:119], 0
	v_mov_b64_e32 v[120:121], 0
	v_mov_b64_e32 v[122:123], 0
	v_mov_b64_e32 v[124:125], 0
	v_mov_b64_e32 v[126:127], 0
	v_mov_b64_e32 v[128:129], 0
	v_mov_b64_e32 v[130:131], 0
	v_mov_b64_e32 v[132:133], 0
	v_mov_b64_e32 v[134:135], 0
	v_mov_b64_e32 v[136:137], 0
	v_mov_b64_e32 v[138:139], 0
	v_mov_b64_e32 v[140:141], 0
	v_mov_b64_e32 v[142:143], 0
	v_mov_b64_e32 v[144:145], 0
	v_mov_b64_e32 v[146:147], 0
	v_mov_b64_e32 v[148:149], 0
	v_mov_b64_e32 v[150:151], 0
	v_mov_b64_e32 v[152:153], 0
	v_mov_b64_e32 v[154:155], 0
	v_mov_b64_e32 v[156:157], 0
	v_mov_b64_e32 v[158:159], 0
	v_add_u32_e32 v202, 0x18000, v188
	v_add_u32_e32 v203, 0x1c000, v188
.LBB0_705:
	ds_read_b128 v[24:27], v191
	ds_read_b128 v[28:31], v191 offset:1024
	ds_read_b128 v[16:19], v191 offset:2048
	ds_read_b128 v[20:23], v191 offset:3072
	ds_read_b128 v[8:11], v192
	ds_read_b128 v[12:15], v192 offset:1024
	ds_read_b128 v[0:3], v192 offset:2048
	ds_read_b128 v[4:7], v192 offset:3072
	s_add_u32 s0, s44, 0xfff80080
	s_addc_u32 s1, s45, -1
	s_cmp_eq_u32 s70, 28
	s_cselect_b32 s49, s60, s1
	s_cselect_b32 s48, s66, s0
	s_cselect_b32 s47, s31, s69
	s_cselect_b32 s46, s67, s68
	s_add_i32 m0, s41, 0xc000
	ds_read_b128 v[178:181], v193
	ds_read_b128 v[182:185], v193 offset:1024
	ds_read_b128 v[194:197], v193 offset:2048
	ds_read_b128 v[198:201], v193 offset:3072
	ds_read_b128 v[208:211], v193 offset:4096
	ds_read_b128 v[212:215], v193 offset:5120
	ds_read_b128 v[216:219], v193 offset:6144
	global_load_lds_dwordx4 v170, s[44:45]
	s_add_i32 m0, s41, 0xe000
	ds_read_b128 v[220:223], v193 offset:7168
	global_load_lds_dwordx4 v172, s[44:45]
	s_waitcnt vmcnt(8)
	s_waitcnt lgkmcnt(0)
	s_setprio 3
	s_barrier
	v_mfma_scale_f32_16x16x128_f8f6f4 v[156:159], v[24:31], v[178:185], v[156:159], v186, v186 op_sel_hi:[0,0,0]
	v_mfma_scale_f32_16x16x128_f8f6f4 v[152:155], v[16:23], v[178:185], v[152:155], v186, v186 op_sel_hi:[0,0,0]
	v_mfma_scale_f32_16x16x128_f8f6f4 v[140:143], v[24:31], v[194:201], v[140:143], v186, v186 op_sel_hi:[0,0,0]
	v_mfma_scale_f32_16x16x128_f8f6f4 v[136:139], v[16:23], v[194:201], v[136:139], v186, v186 op_sel_hi:[0,0,0]
	v_mfma_scale_f32_16x16x128_f8f6f4 v[124:127], v[24:31], v[208:215], v[124:127], v186, v186 op_sel_hi:[0,0,0]
	v_mfma_scale_f32_16x16x128_f8f6f4 v[120:123], v[16:23], v[208:215], v[120:123], v186, v186 op_sel_hi:[0,0,0]
	v_mfma_scale_f32_16x16x128_f8f6f4 v[108:111], v[24:31], v[216:223], v[108:111], v186, v186 op_sel_hi:[0,0,0]
	v_mfma_scale_f32_16x16x128_f8f6f4 v[104:107], v[16:23], v[216:223], v[104:107], v186, v186 op_sel_hi:[0,0,0]
	s_setprio 0
	s_setprio 3
	v_mfma_scale_f32_16x16x128_f8f6f4 v[148:151], v[8:15], v[178:185], v[148:151], v186, v186 op_sel_hi:[0,0,0]
	v_mfma_scale_f32_16x16x128_f8f6f4 v[144:147], v[0:7], v[178:185], v[144:147], v186, v186 op_sel_hi:[0,0,0]
	v_mfma_scale_f32_16x16x128_f8f6f4 v[132:135], v[8:15], v[194:201], v[132:135], v186, v186 op_sel_hi:[0,0,0]
	v_mfma_scale_f32_16x16x128_f8f6f4 v[128:131], v[0:7], v[194:201], v[128:131], v186, v186 op_sel_hi:[0,0,0]
	v_mfma_scale_f32_16x16x128_f8f6f4 v[116:119], v[8:15], v[208:215], v[116:119], v186, v186 op_sel_hi:[0,0,0]
	v_mfma_scale_f32_16x16x128_f8f6f4 v[112:115], v[0:7], v[208:215], v[112:115], v186, v186 op_sel_hi:[0,0,0]
	v_mfma_scale_f32_16x16x128_f8f6f4 v[100:103], v[8:15], v[216:223], v[100:103], v186, v186 op_sel_hi:[0,0,0]
	v_mfma_scale_f32_16x16x128_f8f6f4 v[96:99], v[0:7], v[216:223], v[96:99], v186, v186 op_sel_hi:[0,0,0]
	s_barrier
	s_setprio 0
	s_add_i32 s0, s58, s51
	s_mov_b32 m0, s0
	ds_read_b128 v[194:197], v193 offset:16384
	ds_read_b128 v[198:201], v193 offset:17408
	ds_read_b128 v[208:211], v193 offset:18432
	ds_read_b128 v[212:215], v193 offset:19456
	ds_read_b128 v[216:219], v193 offset:20480
	global_load_lds_dwordx4 v162, s[46:47]
	s_add_i32 m0, s0, 0x2000
	s_add_u32 s0, s46, 0x80000
	s_addc_u32 s1, s47, 0
	s_add_i32 s71, s59, s51
	global_load_lds_dwordx4 v166, s[46:47]
	s_mov_b32 m0, s71
	s_nop 0
	global_load_lds_dwordx4 v162, s[0:1]
	s_add_i32 m0, s71, 0x2000
	ds_read_b128 v[228:231], v193 offset:23552
	global_load_lds_dwordx4 v166, s[0:1]
	s_mov_b32 m0, s41
	ds_read_b128 v[224:227], v193 offset:22528
	global_load_lds_dwordx4 v160, s[48:49]
	s_mov_b32 m0, s43
	ds_read_b128 v[220:223], v193 offset:21504
	global_load_lds_dwordx4 v164, s[48:49]
	s_waitcnt vmcnt(8)
	s_waitcnt lgkmcnt(0)
	s_setprio 3
	s_barrier
	v_mfma_scale_f32_16x16x128_f8f6f4 v[92:95], v[24:31], v[194:201], v[92:95], v186, v186 op_sel_hi:[0,0,0]
	v_mfma_scale_f32_16x16x128_f8f6f4 v[88:91], v[16:23], v[194:201], v[88:91], v186, v186 op_sel_hi:[0,0,0]
	v_mfma_scale_f32_16x16x128_f8f6f4 v[80:83], v[24:31], v[208:215], v[80:83], v186, v186 op_sel_hi:[0,0,0]
	v_mfma_scale_f32_16x16x128_f8f6f4 v[72:75], v[16:23], v[208:215], v[72:75], v186, v186 op_sel_hi:[0,0,0]
	v_mfma_scale_f32_16x16x128_f8f6f4 v[64:67], v[24:31], v[216:223], v[64:67], v186, v186 op_sel_hi:[0,0,0]
	v_mfma_scale_f32_16x16x128_f8f6f4 v[56:59], v[16:23], v[216:223], v[56:59], v186, v186 op_sel_hi:[0,0,0]
	v_mfma_scale_f32_16x16x128_f8f6f4 v[48:51], v[24:31], v[224:231], v[48:51], v186, v186 op_sel_hi:[0,0,0]
	v_mfma_scale_f32_16x16x128_f8f6f4 v[40:43], v[16:23], v[224:231], v[40:43], v186, v186 op_sel_hi:[0,0,0]
	s_setprio 0
	s_setprio 3
	v_mfma_scale_f32_16x16x128_f8f6f4 v[84:87], v[8:15], v[194:201], v[84:87], v186, v186 op_sel_hi:[0,0,0]
	v_mfma_scale_f32_16x16x128_f8f6f4 v[76:79], v[0:7], v[194:201], v[76:79], v186, v186 op_sel_hi:[0,0,0]
	v_mfma_scale_f32_16x16x128_f8f6f4 v[68:71], v[8:15], v[208:215], v[68:71], v186, v186 op_sel_hi:[0,0,0]
	v_mfma_scale_f32_16x16x128_f8f6f4 v[60:63], v[0:7], v[208:215], v[60:63], v186, v186 op_sel_hi:[0,0,0]
	v_mfma_scale_f32_16x16x128_f8f6f4 v[52:55], v[8:15], v[216:223], v[52:55], v186, v186 op_sel_hi:[0,0,0]
	v_mfma_scale_f32_16x16x128_f8f6f4 v[44:47], v[0:7], v[216:223], v[44:47], v186, v186 op_sel_hi:[0,0,0]
	v_mfma_scale_f32_16x16x128_f8f6f4 v[36:39], v[8:15], v[224:231], v[36:39], v186, v186 op_sel_hi:[0,0,0]
	v_mfma_scale_f32_16x16x128_f8f6f4 v[32:35], v[0:7], v[224:231], v[32:35], v186, v186 op_sel_hi:[0,0,0]
	s_barrier
	s_setprio 0
	s_add_i32 s71, 0, 0x18000
	s_add_i32 s73, 0, 0x1c000
	ds_read_b128 v[0:3], v202
	ds_read_b128 v[4:7], v202 offset:1024
	ds_read_b128 v[8:11], v202 offset:2048
	ds_read_b128 v[12:15], v202 offset:3072
	ds_read_b128 v[16:19], v203
	ds_read_b128 v[20:23], v203 offset:1024
	ds_read_b128 v[24:27], v203 offset:2048
	ds_read_b128 v[28:31], v203 offset:3072
	s_add_u32 s0, s48, 0x80000
	s_addc_u32 s1, s49, 0
	s_mov_b32 m0, s52
	ds_read_b128 v[194:197], v193 offset:32768
	ds_read_b128 v[198:201], v193 offset:33792
	ds_read_b128 v[208:211], v193 offset:34816
	ds_read_b128 v[212:215], v193 offset:35840
	ds_read_b128 v[216:219], v193 offset:36864
	ds_read_b128 v[220:223], v193 offset:37888
	ds_read_b128 v[224:227], v193 offset:38912
	global_load_lds_dwordx4 v160, s[0:1]
	s_mov_b32 m0, s53
	ds_read_b128 v[228:231], v193 offset:39936
	global_load_lds_dwordx4 v164, s[0:1]
	s_waitcnt vmcnt(8)
	s_waitcnt lgkmcnt(0)
	s_setprio 3
	s_barrier
	v_mfma_scale_f32_16x16x128_f8f6f4 v[156:159], v[0:7], v[194:201], v[156:159], v186, v186 op_sel_hi:[0,0,0]
	v_mfma_scale_f32_16x16x128_f8f6f4 v[152:155], v[8:15], v[194:201], v[152:155], v186, v186 op_sel_hi:[0,0,0]
	v_mfma_scale_f32_16x16x128_f8f6f4 v[140:143], v[0:7], v[208:215], v[140:143], v186, v186 op_sel_hi:[0,0,0]
	v_mfma_scale_f32_16x16x128_f8f6f4 v[136:139], v[8:15], v[208:215], v[136:139], v186, v186 op_sel_hi:[0,0,0]
	v_mfma_scale_f32_16x16x128_f8f6f4 v[124:127], v[0:7], v[216:223], v[124:127], v186, v186 op_sel_hi:[0,0,0]
	v_mfma_scale_f32_16x16x128_f8f6f4 v[120:123], v[8:15], v[216:223], v[120:123], v186, v186 op_sel_hi:[0,0,0]
	v_mfma_scale_f32_16x16x128_f8f6f4 v[108:111], v[0:7], v[224:231], v[108:111], v186, v186 op_sel_hi:[0,0,0]
	v_mfma_scale_f32_16x16x128_f8f6f4 v[104:107], v[8:15], v[224:231], v[104:107], v186, v186 op_sel_hi:[0,0,0]
	s_setprio 0
	s_setprio 3
	v_mfma_scale_f32_16x16x128_f8f6f4 v[148:151], v[16:23], v[194:201], v[148:151], v186, v186 op_sel_hi:[0,0,0]
	v_mfma_scale_f32_16x16x128_f8f6f4 v[144:147], v[24:31], v[194:201], v[144:147], v186, v186 op_sel_hi:[0,0,0]
	v_mfma_scale_f32_16x16x128_f8f6f4 v[132:135], v[16:23], v[208:215], v[132:135], v186, v186 op_sel_hi:[0,0,0]
	v_mfma_scale_f32_16x16x128_f8f6f4 v[128:131], v[24:31], v[208:215], v[128:131], v186, v186 op_sel_hi:[0,0,0]
	v_mfma_scale_f32_16x16x128_f8f6f4 v[116:119], v[16:23], v[216:223], v[116:119], v186, v186 op_sel_hi:[0,0,0]
	v_mfma_scale_f32_16x16x128_f8f6f4 v[112:115], v[24:31], v[216:223], v[112:115], v186, v186 op_sel_hi:[0,0,0]
	v_mfma_scale_f32_16x16x128_f8f6f4 v[100:103], v[16:23], v[224:231], v[100:103], v186, v186 op_sel_hi:[0,0,0]
	v_mfma_scale_f32_16x16x128_f8f6f4 v[96:99], v[24:31], v[224:231], v[96:99], v186, v186 op_sel_hi:[0,0,0]
	s_barrier
	s_setprio 0
	s_add_i32 s0, s71, s51
	s_add_u32 s100, s46, 0x80
	s_addc_u32 s101, s47, 0
	s_mov_b32 m0, s0
	ds_read_b128 v[194:197], v193 offset:49152
	ds_read_b128 v[198:201], v193 offset:50176
	ds_read_b128 v[208:211], v193 offset:51200
	ds_read_b128 v[212:215], v193 offset:52224
	global_load_lds_dwordx4 v162, s[100:101]
	s_add_i32 m0, s0, 0x2000
	s_add_u32 s100, s46, 0x80
	s_addc_u32 s101, s47, 0
	s_add_u32 s0, s46, 0x80080
	s_addc_u32 s1, s47, 0
	s_add_i32 s46, s73, s51
	global_load_lds_dwordx4 v166, s[100:101]
	s_mov_b32 m0, s46
	ds_read_b128 v[228:231], v193 offset:56320
	global_load_lds_dwordx4 v162, s[0:1]
	s_add_i32 m0, s46, 0x2000
	ds_read_b128 v[224:227], v193 offset:55296
	global_load_lds_dwordx4 v166, s[0:1]
	s_add_u32 s100, s48, 0x80
	s_addc_u32 s101, s49, 0
	s_mov_b32 m0, s55
	ds_read_b128 v[220:223], v193 offset:54272
	global_load_lds_dwordx4 v160, s[100:101]
	s_add_u32 s100, s48, 0x80
	s_addc_u32 s101, s49, 0
	s_mov_b32 m0, s56
	ds_read_b128 v[216:219], v193 offset:53248
	global_load_lds_dwordx4 v164, s[100:101]
	s_waitcnt vmcnt(8)
	s_waitcnt lgkmcnt(0)
	s_setprio 3
	s_barrier
	v_mfma_scale_f32_16x16x128_f8f6f4 v[92:95], v[0:7], v[194:201], v[92:95], v186, v186 op_sel_hi:[0,0,0]
	v_mfma_scale_f32_16x16x128_f8f6f4 v[88:91], v[8:15], v[194:201], v[88:91], v186, v186 op_sel_hi:[0,0,0]
	v_mfma_scale_f32_16x16x128_f8f6f4 v[80:83], v[0:7], v[208:215], v[80:83], v186, v186 op_sel_hi:[0,0,0]
	v_mfma_scale_f32_16x16x128_f8f6f4 v[72:75], v[8:15], v[208:215], v[72:75], v186, v186 op_sel_hi:[0,0,0]
	v_mfma_scale_f32_16x16x128_f8f6f4 v[64:67], v[0:7], v[216:223], v[64:67], v186, v186 op_sel_hi:[0,0,0]
	v_mfma_scale_f32_16x16x128_f8f6f4 v[56:59], v[8:15], v[216:223], v[56:59], v186, v186 op_sel_hi:[0,0,0]
	v_mfma_scale_f32_16x16x128_f8f6f4 v[48:51], v[0:7], v[224:231], v[48:51], v186, v186 op_sel_hi:[0,0,0]
	v_mfma_scale_f32_16x16x128_f8f6f4 v[40:43], v[8:15], v[224:231], v[40:43], v186, v186 op_sel_hi:[0,0,0]
	s_setprio 0
	s_setprio 3
	v_mfma_scale_f32_16x16x128_f8f6f4 v[84:87], v[16:23], v[194:201], v[84:87], v186, v186 op_sel_hi:[0,0,0]
	v_mfma_scale_f32_16x16x128_f8f6f4 v[76:79], v[24:31], v[194:201], v[76:79], v186, v186 op_sel_hi:[0,0,0]
	v_mfma_scale_f32_16x16x128_f8f6f4 v[68:71], v[16:23], v[208:215], v[68:71], v186, v186 op_sel_hi:[0,0,0]
	v_mfma_scale_f32_16x16x128_f8f6f4 v[60:63], v[24:31], v[208:215], v[60:63], v186, v186 op_sel_hi:[0,0,0]
	v_mfma_scale_f32_16x16x128_f8f6f4 v[52:55], v[16:23], v[216:223], v[52:55], v186, v186 op_sel_hi:[0,0,0]
	v_mfma_scale_f32_16x16x128_f8f6f4 v[44:47], v[24:31], v[216:223], v[44:47], v186, v186 op_sel_hi:[0,0,0]
	v_mfma_scale_f32_16x16x128_f8f6f4 v[36:39], v[16:23], v[224:231], v[36:39], v186, v186 op_sel_hi:[0,0,0]
	v_mfma_scale_f32_16x16x128_f8f6f4 v[32:35], v[24:31], v[224:231], v[32:35], v186, v186 op_sel_hi:[0,0,0]
	s_barrier
	s_setprio 0
	s_add_u32 s44, s44, 0x100
	s_addc_u32 s45, s45, 0
	s_add_i32 s70, s70, 2
	s_add_u32 s68, s68, 0x100
	s_addc_u32 s69, s69, 0
	s_cmp_gt_u32 s70, 29
	s_cbranch_scc0 .LBB0_705
	s_and_b64 vcc, exec, s[12:13]
	s_cbranch_vccz .LBB0_708
	s_barrier

.LBB0_1636:
	s_ashr_i32 s35, s34, 31
	s_lshl_b64 s[0:1], s[34:35], 21
	s_add_u32 s36, s25, s0
	s_addc_u32 s37, s26, s1
	s_and_b64 s[0:1], s[4:5], exec
	s_cselect_b32 s35, s37, s43
	s_cselect_b32 s64, s36, s42
	s_ashr_i32 s31, s30, 31
	s_lshl_b64 s[0:1], s[30:31], 21
	s_add_u32 s38, s27, s0
	s_addc_u32 s39, s48, s1
	s_and_b64 s[0:1], s[4:5], exec
	s_cselect_b32 s31, s39, s45
	s_cselect_b32 s65, s38, s44
	s_add_u32 s42, s42, 0x100080
	s_addc_u32 s43, s43, 0
	s_add_u32 s66, s44, 0x100
	v_mov_b32_e32 v0, 0
	s_addc_u32 s67, s45, 0
	s_mov_b32 s68, -2
	v_mov_b64_e32 v[0:1], 0
	v_mov_b64_e32 v[2:3], 0
	v_mov_b64_e32 v[4:5], 0
	v_mov_b64_e32 v[6:7], 0
	v_mov_b64_e32 v[8:9], 0
	v_mov_b64_e32 v[10:11], 0
	v_mov_b64_e32 v[12:13], 0
	v_mov_b64_e32 v[14:15], 0
	v_mov_b64_e32 v[16:17], 0
	v_mov_b64_e32 v[18:19], 0
	v_mov_b64_e32 v[20:21], 0
	v_mov_b64_e32 v[22:23], 0
	v_mov_b64_e32 v[24:25], 0
	v_mov_b64_e32 v[26:27], 0
	v_mov_b64_e32 v[28:29], 0
	v_mov_b64_e32 v[30:31], 0
	v_mov_b64_e32 v[32:33], 0
	v_mov_b64_e32 v[34:35], 0
	v_mov_b64_e32 v[36:37], 0
	v_mov_b64_e32 v[38:39], 0
	v_mov_b64_e32 v[40:41], 0
	v_mov_b64_e32 v[42:43], 0
	v_mov_b64_e32 v[44:45], 0
	v_mov_b64_e32 v[46:47], 0
	v_mov_b64_e32 v[48:49], 0
	v_mov_b64_e32 v[50:51], 0
	v_mov_b64_e32 v[52:53], 0
	v_mov_b64_e32 v[54:55], 0
	v_mov_b64_e32 v[56:57], 0
	v_mov_b64_e32 v[58:59], 0
	v_mov_b64_e32 v[60:61], 0
	v_mov_b64_e32 v[62:63], 0
	v_mov_b64_e32 v[64:65], 0
	v_mov_b64_e32 v[66:67], 0
	v_mov_b64_e32 v[68:69], 0
	v_mov_b64_e32 v[70:71], 0
	v_mov_b64_e32 v[72:73], 0
	v_mov_b64_e32 v[74:75], 0
	v_mov_b64_e32 v[76:77], 0
	v_mov_b64_e32 v[78:79], 0
	v_mov_b64_e32 v[80:81], 0
	v_mov_b64_e32 v[82:83], 0
	v_mov_b64_e32 v[84:85], 0
	v_mov_b64_e32 v[86:87], 0
	v_mov_b64_e32 v[88:89], 0
	v_mov_b64_e32 v[90:91], 0
	v_mov_b64_e32 v[92:93], 0
	v_mov_b64_e32 v[94:95], 0
	v_mov_b64_e32 v[96:97], 0
	v_mov_b64_e32 v[98:99], 0
	v_mov_b64_e32 v[100:101], 0
	v_mov_b64_e32 v[102:103], 0
	v_mov_b64_e32 v[104:105], 0
	v_mov_b64_e32 v[106:107], 0
	v_mov_b64_e32 v[108:109], 0
	v_mov_b64_e32 v[110:111], 0
	v_mov_b64_e32 v[112:113], 0
	v_mov_b64_e32 v[114:115], 0
	v_mov_b64_e32 v[116:117], 0
	v_mov_b64_e32 v[118:119], 0
	v_mov_b64_e32 v[120:121], 0
	v_mov_b64_e32 v[122:123], 0
	v_mov_b64_e32 v[124:125], 0
	v_mov_b64_e32 v[126:127], 0
	v_add_u32_e32 v228, 0x18000, v147
	v_add_u32_e32 v229, 0x1c000, v147
.LBB0_1637:
	ds_read_b128 v[152:155], v149
	ds_read_b128 v[156:159], v149 offset:1024
	ds_read_b128 v[160:163], v149 offset:2048
	ds_read_b128 v[164:167], v149 offset:3072
	ds_read_b128 v[168:171], v150
	ds_read_b128 v[172:175], v150 offset:1024
	ds_read_b128 v[176:179], v150 offset:2048
	ds_read_b128 v[180:183], v150 offset:3072
	s_add_u32 s0, s42, 0xfff00080
	s_addc_u32 s1, s43, -1
	s_cmp_eq_u32 s68, 60
	s_cselect_b32 s47, s35, s1
	s_cselect_b32 s46, s64, s0
	s_cselect_b32 s45, s31, s67
	s_cselect_b32 s44, s65, s66
	s_add_i32 m0, s41, 0xc000
	ds_read_b128 v[184:187], v151
	ds_read_b128 v[188:191], v151 offset:1024
	ds_read_b128 v[192:195], v151 offset:2048
	ds_read_b128 v[196:199], v151 offset:3072
	ds_read_b128 v[200:203], v151 offset:4096
	ds_read_b128 v[210:213], v151 offset:5120
	ds_read_b128 v[214:217], v151 offset:6144
	global_load_lds_dwordx4 v136, s[42:43]
	s_add_i32 m0, s41, 0xe000
	ds_read_b128 v[218:221], v151 offset:7168
	global_load_lds_dwordx4 v138, s[42:43]
	s_waitcnt vmcnt(8)
	s_waitcnt lgkmcnt(0)
	s_setprio 3
	s_barrier
	v_mfma_f32_16x16x32_bf16 v[124:127], v[152:155], v[184:187], v[124:127]
	v_mfma_f32_16x16x32_bf16 v[120:123], v[160:163], v[184:187], v[120:123]
	v_mfma_f32_16x16x32_bf16 v[116:119], v[152:155], v[192:195], v[116:119]
	v_mfma_f32_16x16x32_bf16 v[108:111], v[160:163], v[192:195], v[108:111]
	v_mfma_f32_16x16x32_bf16 v[100:103], v[152:155], v[200:203], v[100:103]
	v_mfma_f32_16x16x32_bf16 v[92:95], v[160:163], v[200:203], v[92:95]
	v_mfma_f32_16x16x32_bf16 v[84:87], v[152:155], v[214:217], v[84:87]
	v_mfma_f32_16x16x32_bf16 v[76:79], v[160:163], v[214:217], v[76:79]
	v_mfma_f32_16x16x32_bf16 v[124:127], v[156:159], v[188:191], v[124:127]
	v_mfma_f32_16x16x32_bf16 v[120:123], v[164:167], v[188:191], v[120:123]
	v_mfma_f32_16x16x32_bf16 v[116:119], v[156:159], v[196:199], v[116:119]
	v_mfma_f32_16x16x32_bf16 v[108:111], v[164:167], v[196:199], v[108:111]
	v_mfma_f32_16x16x32_bf16 v[100:103], v[156:159], v[210:213], v[100:103]
	v_mfma_f32_16x16x32_bf16 v[92:95], v[164:167], v[210:213], v[92:95]
	v_mfma_f32_16x16x32_bf16 v[84:87], v[156:159], v[218:221], v[84:87]
	v_mfma_f32_16x16x32_bf16 v[76:79], v[164:167], v[218:221], v[76:79]
	s_setprio 0
	s_setprio 3
	v_mfma_f32_16x16x32_bf16 v[112:115], v[168:171], v[184:187], v[112:115]
	v_mfma_f32_16x16x32_bf16 v[104:107], v[176:179], v[184:187], v[104:107]
	v_mfma_f32_16x16x32_bf16 v[96:99], v[168:171], v[192:195], v[96:99]
	v_mfma_f32_16x16x32_bf16 v[88:91], v[176:179], v[192:195], v[88:91]
	v_mfma_f32_16x16x32_bf16 v[80:83], v[168:171], v[200:203], v[80:83]
	v_mfma_f32_16x16x32_bf16 v[72:75], v[176:179], v[200:203], v[72:75]
	v_mfma_f32_16x16x32_bf16 v[68:71], v[168:171], v[214:217], v[68:71]
	v_mfma_f32_16x16x32_bf16 v[64:67], v[176:179], v[214:217], v[64:67]
	v_mfma_f32_16x16x32_bf16 v[112:115], v[172:175], v[188:191], v[112:115]
	v_mfma_f32_16x16x32_bf16 v[104:107], v[180:183], v[188:191], v[104:107]
	v_mfma_f32_16x16x32_bf16 v[96:99], v[172:175], v[196:199], v[96:99]
	v_mfma_f32_16x16x32_bf16 v[88:91], v[180:183], v[196:199], v[88:91]
	v_mfma_f32_16x16x32_bf16 v[80:83], v[172:175], v[210:213], v[80:83]
	v_mfma_f32_16x16x32_bf16 v[72:75], v[180:183], v[210:213], v[72:75]
	v_mfma_f32_16x16x32_bf16 v[68:71], v[172:175], v[218:221], v[68:71]
	v_mfma_f32_16x16x32_bf16 v[64:67], v[180:183], v[218:221], v[64:67]
	s_barrier
	s_setprio 0
	s_add_i32 s0, s57, s49
	s_mov_b32 m0, s0
	ds_read_b128 v[184:187], v151 offset:16384
	ds_read_b128 v[188:191], v151 offset:17408
	ds_read_b128 v[192:195], v151 offset:18432
	ds_read_b128 v[196:199], v151 offset:19456
	ds_read_b128 v[200:203], v151 offset:20480
	global_load_lds_dwordx4 v130, s[44:45]
	s_add_i32 m0, s0, 0x2000
	s_add_u32 s0, s44, 0x100000
	s_addc_u32 s1, s45, 0
	s_add_i32 s69, s58, s49
	global_load_lds_dwordx4 v134, s[44:45]
	s_mov_b32 m0, s69
	s_nop 0
	global_load_lds_dwordx4 v130, s[0:1]
	s_add_i32 m0, s69, 0x2000
	ds_read_b128 v[218:221], v151 offset:23552
	global_load_lds_dwordx4 v134, s[0:1]
	s_mov_b32 m0, s41
	ds_read_b128 v[214:217], v151 offset:22528
	global_load_lds_dwordx4 v128, s[46:47]
	s_mov_b32 m0, s50
	ds_read_b128 v[210:213], v151 offset:21504
	global_load_lds_dwordx4 v132, s[46:47]
	s_waitcnt vmcnt(8)
	s_waitcnt lgkmcnt(0)
	s_setprio 3
	s_barrier
	v_mfma_f32_16x16x32_bf16 v[60:63], v[152:155], v[184:187], v[60:63]
	v_mfma_f32_16x16x32_bf16 v[56:59], v[160:163], v[184:187], v[56:59]
	v_mfma_f32_16x16x32_bf16 v[52:55], v[152:155], v[192:195], v[52:55]
	v_mfma_f32_16x16x32_bf16 v[44:47], v[160:163], v[192:195], v[44:47]
	v_mfma_f32_16x16x32_bf16 v[36:39], v[152:155], v[200:203], v[36:39]
	v_mfma_f32_16x16x32_bf16 v[28:31], v[160:163], v[200:203], v[28:31]
	v_mfma_f32_16x16x32_bf16 v[20:23], v[152:155], v[214:217], v[20:23]
	v_mfma_f32_16x16x32_bf16 v[12:15], v[160:163], v[214:217], v[12:15]
	v_mfma_f32_16x16x32_bf16 v[60:63], v[156:159], v[188:191], v[60:63]
	v_mfma_f32_16x16x32_bf16 v[56:59], v[164:167], v[188:191], v[56:59]
	v_mfma_f32_16x16x32_bf16 v[52:55], v[156:159], v[196:199], v[52:55]
	v_mfma_f32_16x16x32_bf16 v[44:47], v[164:167], v[196:199], v[44:47]
	v_mfma_f32_16x16x32_bf16 v[36:39], v[156:159], v[210:213], v[36:39]
	v_mfma_f32_16x16x32_bf16 v[28:31], v[164:167], v[210:213], v[28:31]
	v_mfma_f32_16x16x32_bf16 v[20:23], v[156:159], v[218:221], v[20:23]
	v_mfma_f32_16x16x32_bf16 v[12:15], v[164:167], v[218:221], v[12:15]
	s_setprio 0
	s_setprio 3
	v_mfma_f32_16x16x32_bf16 v[48:51], v[168:171], v[184:187], v[48:51]
	v_mfma_f32_16x16x32_bf16 v[40:43], v[176:179], v[184:187], v[40:43]
	v_mfma_f32_16x16x32_bf16 v[32:35], v[168:171], v[192:195], v[32:35]
	v_mfma_f32_16x16x32_bf16 v[24:27], v[176:179], v[192:195], v[24:27]
	v_mfma_f32_16x16x32_bf16 v[16:19], v[168:171], v[200:203], v[16:19]
	v_mfma_f32_16x16x32_bf16 v[8:11], v[176:179], v[200:203], v[8:11]
	v_mfma_f32_16x16x32_bf16 v[4:7], v[168:171], v[214:217], v[4:7]
	v_mfma_f32_16x16x32_bf16 v[0:3], v[176:179], v[214:217], v[0:3]
	v_mfma_f32_16x16x32_bf16 v[48:51], v[172:175], v[188:191], v[48:51]
	v_mfma_f32_16x16x32_bf16 v[40:43], v[180:183], v[188:191], v[40:43]
	v_mfma_f32_16x16x32_bf16 v[32:35], v[172:175], v[196:199], v[32:35]
	v_mfma_f32_16x16x32_bf16 v[24:27], v[180:183], v[196:199], v[24:27]
	v_mfma_f32_16x16x32_bf16 v[16:19], v[172:175], v[210:213], v[16:19]
	v_mfma_f32_16x16x32_bf16 v[8:11], v[180:183], v[210:213], v[8:11]
	v_mfma_f32_16x16x32_bf16 v[4:7], v[172:175], v[218:221], v[4:7]
	v_mfma_f32_16x16x32_bf16 v[0:3], v[180:183], v[218:221], v[0:3]
	s_barrier
	s_setprio 0
	s_add_i32 s69, 0, 0x18000
	s_add_i32 s70, 0, 0x1c000
	ds_read_b128 v[152:155], v228
	ds_read_b128 v[156:159], v228 offset:1024
	ds_read_b128 v[160:163], v228 offset:2048
	ds_read_b128 v[164:167], v228 offset:3072
	ds_read_b128 v[168:171], v229
	ds_read_b128 v[172:175], v229 offset:1024
	ds_read_b128 v[176:179], v229 offset:2048
	ds_read_b128 v[180:183], v229 offset:3072
	s_add_u32 s0, s46, 0x100000
	s_addc_u32 s1, s47, 0
	s_mov_b32 m0, s51
	ds_read_b128 v[184:187], v151 offset:32768
	ds_read_b128 v[188:191], v151 offset:33792
	ds_read_b128 v[192:195], v151 offset:34816
	ds_read_b128 v[196:199], v151 offset:35840
	ds_read_b128 v[200:203], v151 offset:36864
	ds_read_b128 v[210:213], v151 offset:37888
	ds_read_b128 v[214:217], v151 offset:38912
	global_load_lds_dwordx4 v128, s[0:1]
	s_mov_b32 m0, s52
	ds_read_b128 v[218:221], v151 offset:39936
	global_load_lds_dwordx4 v132, s[0:1]
	s_waitcnt vmcnt(8)
	s_waitcnt lgkmcnt(0)
	s_setprio 3
	s_barrier
	v_mfma_f32_16x16x32_bf16 v[124:127], v[152:155], v[184:187], v[124:127]
	v_mfma_f32_16x16x32_bf16 v[120:123], v[160:163], v[184:187], v[120:123]
	v_mfma_f32_16x16x32_bf16 v[116:119], v[152:155], v[192:195], v[116:119]
	v_mfma_f32_16x16x32_bf16 v[108:111], v[160:163], v[192:195], v[108:111]
	v_mfma_f32_16x16x32_bf16 v[100:103], v[152:155], v[200:203], v[100:103]
	v_mfma_f32_16x16x32_bf16 v[92:95], v[160:163], v[200:203], v[92:95]
	v_mfma_f32_16x16x32_bf16 v[84:87], v[152:155], v[214:217], v[84:87]
	v_mfma_f32_16x16x32_bf16 v[76:79], v[160:163], v[214:217], v[76:79]
	v_mfma_f32_16x16x32_bf16 v[124:127], v[156:159], v[188:191], v[124:127]
	v_mfma_f32_16x16x32_bf16 v[120:123], v[164:167], v[188:191], v[120:123]
	v_mfma_f32_16x16x32_bf16 v[116:119], v[156:159], v[196:199], v[116:119]
	v_mfma_f32_16x16x32_bf16 v[108:111], v[164:167], v[196:199], v[108:111]
	v_mfma_f32_16x16x32_bf16 v[100:103], v[156:159], v[210:213], v[100:103]
	v_mfma_f32_16x16x32_bf16 v[92:95], v[164:167], v[210:213], v[92:95]
	v_mfma_f32_16x16x32_bf16 v[84:87], v[156:159], v[218:221], v[84:87]
	v_mfma_f32_16x16x32_bf16 v[76:79], v[164:167], v[218:221], v[76:79]
	s_setprio 0
	s_setprio 3
	v_mfma_f32_16x16x32_bf16 v[112:115], v[168:171], v[184:187], v[112:115]
	v_mfma_f32_16x16x32_bf16 v[104:107], v[176:179], v[184:187], v[104:107]
	v_mfma_f32_16x16x32_bf16 v[96:99], v[168:171], v[192:195], v[96:99]
	v_mfma_f32_16x16x32_bf16 v[88:91], v[176:179], v[192:195], v[88:91]
	v_mfma_f32_16x16x32_bf16 v[80:83], v[168:171], v[200:203], v[80:83]
	v_mfma_f32_16x16x32_bf16 v[72:75], v[176:179], v[200:203], v[72:75]
	v_mfma_f32_16x16x32_bf16 v[68:71], v[168:171], v[214:217], v[68:71]
	v_mfma_f32_16x16x32_bf16 v[64:67], v[176:179], v[214:217], v[64:67]
	v_mfma_f32_16x16x32_bf16 v[112:115], v[172:175], v[188:191], v[112:115]
	v_mfma_f32_16x16x32_bf16 v[104:107], v[180:183], v[188:191], v[104:107]
	v_mfma_f32_16x16x32_bf16 v[96:99], v[172:175], v[196:199], v[96:99]
	v_mfma_f32_16x16x32_bf16 v[88:91], v[180:183], v[196:199], v[88:91]
	v_mfma_f32_16x16x32_bf16 v[80:83], v[172:175], v[210:213], v[80:83]
	v_mfma_f32_16x16x32_bf16 v[72:75], v[180:183], v[210:213], v[72:75]
	v_mfma_f32_16x16x32_bf16 v[68:71], v[172:175], v[218:221], v[68:71]
	v_mfma_f32_16x16x32_bf16 v[64:67], v[180:183], v[218:221], v[64:67]
	s_barrier
	s_setprio 0
	s_add_i32 s0, s69, s49
	s_add_u32 s100, s44, 0x80
	s_addc_u32 s101, s45, 0
	s_mov_b32 m0, s0
	ds_read_b128 v[184:187], v151 offset:49152
	ds_read_b128 v[188:191], v151 offset:50176
	ds_read_b128 v[192:195], v151 offset:51200
	ds_read_b128 v[196:199], v151 offset:52224
	global_load_lds_dwordx4 v130, s[100:101]
	s_add_i32 m0, s0, 0x2000
	s_add_u32 s100, s44, 0x80
	s_addc_u32 s101, s45, 0
	s_add_u32 s0, s44, 0x100080
	s_addc_u32 s1, s45, 0
	s_add_i32 s44, s70, s49
	global_load_lds_dwordx4 v134, s[100:101]
	s_mov_b32 m0, s44
	ds_read_b128 v[218:221], v151 offset:56320
	global_load_lds_dwordx4 v130, s[0:1]
	s_add_i32 m0, s44, 0x2000
	ds_read_b128 v[214:217], v151 offset:55296
	global_load_lds_dwordx4 v134, s[0:1]
	s_add_u32 s100, s46, 0x80
	s_addc_u32 s101, s47, 0
	s_mov_b32 m0, s54
	ds_read_b128 v[210:213], v151 offset:54272
	global_load_lds_dwordx4 v128, s[100:101]
	s_add_u32 s100, s46, 0x80
	s_addc_u32 s101, s47, 0
	s_mov_b32 m0, s55
	ds_read_b128 v[200:203], v151 offset:53248
	global_load_lds_dwordx4 v132, s[100:101]
	s_waitcnt vmcnt(8)
	s_waitcnt lgkmcnt(0)
	s_setprio 3
	s_barrier
	v_mfma_f32_16x16x32_bf16 v[60:63], v[152:155], v[184:187], v[60:63]
	v_mfma_f32_16x16x32_bf16 v[56:59], v[160:163], v[184:187], v[56:59]
	v_mfma_f32_16x16x32_bf16 v[52:55], v[152:155], v[192:195], v[52:55]
	v_mfma_f32_16x16x32_bf16 v[44:47], v[160:163], v[192:195], v[44:47]
	v_mfma_f32_16x16x32_bf16 v[36:39], v[152:155], v[200:203], v[36:39]
	v_mfma_f32_16x16x32_bf16 v[28:31], v[160:163], v[200:203], v[28:31]
	v_mfma_f32_16x16x32_bf16 v[20:23], v[152:155], v[214:217], v[20:23]
	v_mfma_f32_16x16x32_bf16 v[12:15], v[160:163], v[214:217], v[12:15]
	v_mfma_f32_16x16x32_bf16 v[60:63], v[156:159], v[188:191], v[60:63]
	v_mfma_f32_16x16x32_bf16 v[56:59], v[164:167], v[188:191], v[56:59]
	v_mfma_f32_16x16x32_bf16 v[52:55], v[156:159], v[196:199], v[52:55]
	v_mfma_f32_16x16x32_bf16 v[44:47], v[164:167], v[196:199], v[44:47]
	v_mfma_f32_16x16x32_bf16 v[36:39], v[156:159], v[210:213], v[36:39]
	v_mfma_f32_16x16x32_bf16 v[28:31], v[164:167], v[210:213], v[28:31]
	v_mfma_f32_16x16x32_bf16 v[20:23], v[156:159], v[218:221], v[20:23]
	v_mfma_f32_16x16x32_bf16 v[12:15], v[164:167], v[218:221], v[12:15]
	s_setprio 0
	s_setprio 3
	v_mfma_f32_16x16x32_bf16 v[48:51], v[168:171], v[184:187], v[48:51]
	v_mfma_f32_16x16x32_bf16 v[40:43], v[176:179], v[184:187], v[40:43]
	v_mfma_f32_16x16x32_bf16 v[32:35], v[168:171], v[192:195], v[32:35]
	v_mfma_f32_16x16x32_bf16 v[24:27], v[176:179], v[192:195], v[24:27]
	v_mfma_f32_16x16x32_bf16 v[16:19], v[168:171], v[200:203], v[16:19]
	v_mfma_f32_16x16x32_bf16 v[8:11], v[176:179], v[200:203], v[8:11]
	v_mfma_f32_16x16x32_bf16 v[4:7], v[168:171], v[214:217], v[4:7]
	v_mfma_f32_16x16x32_bf16 v[0:3], v[176:179], v[214:217], v[0:3]
	v_mfma_f32_16x16x32_bf16 v[48:51], v[172:175], v[188:191], v[48:51]
	v_mfma_f32_16x16x32_bf16 v[40:43], v[180:183], v[188:191], v[40:43]
	v_mfma_f32_16x16x32_bf16 v[32:35], v[172:175], v[196:199], v[32:35]
	v_mfma_f32_16x16x32_bf16 v[24:27], v[180:183], v[196:199], v[24:27]
	v_mfma_f32_16x16x32_bf16 v[16:19], v[172:175], v[210:213], v[16:19]
	v_mfma_f32_16x16x32_bf16 v[8:11], v[180:183], v[210:213], v[8:11]
	v_mfma_f32_16x16x32_bf16 v[4:7], v[172:175], v[218:221], v[4:7]
	v_mfma_f32_16x16x32_bf16 v[0:3], v[180:183], v[218:221], v[0:3]
	s_barrier
	s_setprio 0
	s_add_u32 s42, s42, 0x100
	s_addc_u32 s43, s43, 0
	s_add_i32 s68, s68, 2
	s_add_u32 s66, s66, 0x100
	s_addc_u32 s67, s67, 0
	s_cmp_gt_u32 s68, 61
	s_cbranch_scc0 .LBB0_1637
	s_and_b64 vcc, exec, s[16:17]
	s_cbranch_vccz .LBB0_1640
	s_barrier

.LBB0_1812:
	s_ashr_i32 s19, s18, 31
	s_lshl_b64 s[0:1], s[18:19], 21
	s_add_u32 s20, s25, s0
	s_addc_u32 s21, s26, s1
	s_and_b64 s[0:1], s[6:7], exec
	s_cselect_b32 s59, s21, s37
	s_cselect_b32 s60, s20, s36
	s_ashr_i32 s17, s16, 31
	s_lshl_b64 s[0:1], s[16:17], 21
	s_add_u32 s28, s27, s0
	s_addc_u32 s29, s42, s1
	s_and_b64 s[0:1], s[6:7], exec
	s_cselect_b32 s17, s29, s39
	s_cselect_b32 s61, s28, s38
	s_add_u32 s36, s36, 0x100080
	s_addc_u32 s37, s37, 0
	s_add_u32 s62, s38, 0x100
	v_mov_b32_e32 v0, 0
	s_addc_u32 s63, s39, 0
	s_mov_b32 s64, -2
	v_mov_b64_e32 v[0:1], 0
	v_mov_b64_e32 v[2:3], 0
	v_mov_b64_e32 v[4:5], 0
	v_mov_b64_e32 v[6:7], 0
	v_mov_b64_e32 v[8:9], 0
	v_mov_b64_e32 v[10:11], 0
	v_mov_b64_e32 v[12:13], 0
	v_mov_b64_e32 v[14:15], 0
	v_mov_b64_e32 v[16:17], 0
	v_mov_b64_e32 v[18:19], 0
	v_mov_b64_e32 v[20:21], 0
	v_mov_b64_e32 v[22:23], 0
	v_mov_b64_e32 v[24:25], 0
	v_mov_b64_e32 v[26:27], 0
	v_mov_b64_e32 v[28:29], 0
	v_mov_b64_e32 v[30:31], 0
	v_mov_b64_e32 v[32:33], 0
	v_mov_b64_e32 v[34:35], 0
	v_mov_b64_e32 v[36:37], 0
	v_mov_b64_e32 v[38:39], 0
	v_mov_b64_e32 v[40:41], 0
	v_mov_b64_e32 v[42:43], 0
	v_mov_b64_e32 v[44:45], 0
	v_mov_b64_e32 v[46:47], 0
	v_mov_b64_e32 v[48:49], 0
	v_mov_b64_e32 v[50:51], 0
	v_mov_b64_e32 v[52:53], 0
	v_mov_b64_e32 v[54:55], 0
	v_mov_b64_e32 v[56:57], 0
	v_mov_b64_e32 v[58:59], 0
	v_mov_b64_e32 v[60:61], 0
	v_mov_b64_e32 v[62:63], 0
	v_mov_b64_e32 v[64:65], 0
	v_mov_b64_e32 v[66:67], 0
	v_mov_b64_e32 v[68:69], 0
	v_mov_b64_e32 v[70:71], 0
	v_mov_b64_e32 v[72:73], 0
	v_mov_b64_e32 v[74:75], 0
	v_mov_b64_e32 v[76:77], 0
	v_mov_b64_e32 v[78:79], 0
	v_mov_b64_e32 v[80:81], 0
	v_mov_b64_e32 v[82:83], 0
	v_mov_b64_e32 v[84:85], 0
	v_mov_b64_e32 v[86:87], 0
	v_mov_b64_e32 v[88:89], 0
	v_mov_b64_e32 v[90:91], 0
	v_mov_b64_e32 v[92:93], 0
	v_mov_b64_e32 v[94:95], 0
	v_mov_b64_e32 v[96:97], 0
	v_mov_b64_e32 v[98:99], 0
	v_mov_b64_e32 v[100:101], 0
	v_mov_b64_e32 v[102:103], 0
	v_mov_b64_e32 v[104:105], 0
	v_mov_b64_e32 v[106:107], 0
	v_mov_b64_e32 v[108:109], 0
	v_mov_b64_e32 v[110:111], 0
	v_mov_b64_e32 v[112:113], 0
	v_mov_b64_e32 v[114:115], 0
	v_mov_b64_e32 v[116:117], 0
	v_mov_b64_e32 v[118:119], 0
	v_mov_b64_e32 v[120:121], 0
	v_mov_b64_e32 v[122:123], 0
	v_mov_b64_e32 v[124:125], 0
	v_mov_b64_e32 v[126:127], 0
	v_add_u32_e32 v234, 0x18000, v153
	v_add_u32_e32 v235, 0x1c000, v153
.LBB0_1813:
	ds_read_b128 v[148:151], v156
	ds_read_b128 v[160:163], v156 offset:1024
	ds_read_b128 v[164:167], v156 offset:2048
	ds_read_b128 v[168:171], v156 offset:3072
	ds_read_b128 v[172:175], v157
	ds_read_b128 v[176:179], v157 offset:1024
	ds_read_b128 v[180:183], v157 offset:2048
	ds_read_b128 v[184:187], v157 offset:3072
	s_add_u32 s0, s36, 0xfff00080
	s_addc_u32 s1, s37, -1
	s_cmp_eq_u32 s64, 60
	s_cselect_b32 s41, s59, s1
	s_cselect_b32 s40, s60, s0
	s_cselect_b32 s39, s17, s63
	s_cselect_b32 s38, s61, s62
	s_add_i32 m0, s31, 0xc000
	ds_read_b128 v[188:191], v158
	ds_read_b128 v[192:195], v158 offset:1024
	ds_read_b128 v[196:199], v158 offset:2048
	ds_read_b128 v[200:203], v158 offset:3072
	ds_read_b128 v[210:213], v158 offset:4096
	ds_read_b128 v[214:217], v158 offset:5120
	ds_read_b128 v[218:221], v158 offset:6144
	global_load_lds_dwordx4 v140, s[36:37]
	s_add_i32 m0, s31, 0xe000
	ds_read_b128 v[222:225], v158 offset:7168
	global_load_lds_dwordx4 v142, s[36:37]
	s_waitcnt vmcnt(8)
	s_waitcnt lgkmcnt(0)
	s_setprio 3
	s_barrier
	v_mfma_f32_16x16x32_bf16 v[124:127], v[148:151], v[188:191], v[124:127]
	v_mfma_f32_16x16x32_bf16 v[120:123], v[164:167], v[188:191], v[120:123]
	v_mfma_f32_16x16x32_bf16 v[108:111], v[148:151], v[196:199], v[108:111]
	v_mfma_f32_16x16x32_bf16 v[104:107], v[164:167], v[196:199], v[104:107]
	v_mfma_f32_16x16x32_bf16 v[92:95], v[148:151], v[210:213], v[92:95]
	v_mfma_f32_16x16x32_bf16 v[88:91], v[164:167], v[210:213], v[88:91]
	v_mfma_f32_16x16x32_bf16 v[76:79], v[148:151], v[218:221], v[76:79]
	v_mfma_f32_16x16x32_bf16 v[72:75], v[164:167], v[218:221], v[72:75]
	v_mfma_f32_16x16x32_bf16 v[124:127], v[160:163], v[192:195], v[124:127]
	v_mfma_f32_16x16x32_bf16 v[120:123], v[168:171], v[192:195], v[120:123]
	v_mfma_f32_16x16x32_bf16 v[108:111], v[160:163], v[200:203], v[108:111]
	v_mfma_f32_16x16x32_bf16 v[104:107], v[168:171], v[200:203], v[104:107]
	v_mfma_f32_16x16x32_bf16 v[92:95], v[160:163], v[214:217], v[92:95]
	v_mfma_f32_16x16x32_bf16 v[88:91], v[168:171], v[214:217], v[88:91]
	v_mfma_f32_16x16x32_bf16 v[76:79], v[160:163], v[222:225], v[76:79]
	v_mfma_f32_16x16x32_bf16 v[72:75], v[168:171], v[222:225], v[72:75]
	s_setprio 0
	s_setprio 3
	v_mfma_f32_16x16x32_bf16 v[116:119], v[172:175], v[188:191], v[116:119]
	v_mfma_f32_16x16x32_bf16 v[112:115], v[180:183], v[188:191], v[112:115]
	v_mfma_f32_16x16x32_bf16 v[100:103], v[172:175], v[196:199], v[100:103]
	v_mfma_f32_16x16x32_bf16 v[96:99], v[180:183], v[196:199], v[96:99]
	v_mfma_f32_16x16x32_bf16 v[84:87], v[172:175], v[210:213], v[84:87]
	v_mfma_f32_16x16x32_bf16 v[80:83], v[180:183], v[210:213], v[80:83]
	v_mfma_f32_16x16x32_bf16 v[68:71], v[172:175], v[218:221], v[68:71]
	v_mfma_f32_16x16x32_bf16 v[64:67], v[180:183], v[218:221], v[64:67]
	v_mfma_f32_16x16x32_bf16 v[116:119], v[176:179], v[192:195], v[116:119]
	v_mfma_f32_16x16x32_bf16 v[112:115], v[184:187], v[192:195], v[112:115]
	v_mfma_f32_16x16x32_bf16 v[100:103], v[176:179], v[200:203], v[100:103]
	v_mfma_f32_16x16x32_bf16 v[96:99], v[184:187], v[200:203], v[96:99]
	v_mfma_f32_16x16x32_bf16 v[84:87], v[176:179], v[214:217], v[84:87]
	v_mfma_f32_16x16x32_bf16 v[80:83], v[184:187], v[214:217], v[80:83]
	v_mfma_f32_16x16x32_bf16 v[68:71], v[176:179], v[222:225], v[68:71]
	v_mfma_f32_16x16x32_bf16 v[64:67], v[184:187], v[222:225], v[64:67]
	s_barrier
	s_setprio 0
	s_add_i32 s0, s52, s43
	s_mov_b32 m0, s0
	ds_read_b128 v[188:191], v158 offset:16384
	ds_read_b128 v[192:195], v158 offset:17408
	ds_read_b128 v[196:199], v158 offset:18432
	ds_read_b128 v[200:203], v158 offset:19456
	ds_read_b128 v[210:213], v158 offset:20480
	global_load_lds_dwordx4 v132, s[38:39]
	s_add_i32 m0, s0, 0x2000
	s_add_u32 s0, s38, 0x100000
	s_addc_u32 s1, s39, 0
	s_add_i32 s65, s53, s43
	global_load_lds_dwordx4 v136, s[38:39]
	s_mov_b32 m0, s65
	s_nop 0
	global_load_lds_dwordx4 v132, s[0:1]
	s_add_i32 m0, s65, 0x2000
	ds_read_b128 v[222:225], v158 offset:23552
	global_load_lds_dwordx4 v136, s[0:1]
	s_mov_b32 m0, s31
	ds_read_b128 v[218:221], v158 offset:22528
	global_load_lds_dwordx4 v130, s[40:41]
	s_mov_b32 m0, s35
	ds_read_b128 v[214:217], v158 offset:21504
	global_load_lds_dwordx4 v134, s[40:41]
	s_waitcnt vmcnt(8)
	s_waitcnt lgkmcnt(0)
	s_setprio 3
	s_barrier
	v_mfma_f32_16x16x32_bf16 v[60:63], v[148:151], v[188:191], v[60:63]
	v_mfma_f32_16x16x32_bf16 v[56:59], v[164:167], v[188:191], v[56:59]
	v_mfma_f32_16x16x32_bf16 v[44:47], v[148:151], v[196:199], v[44:47]
	v_mfma_f32_16x16x32_bf16 v[40:43], v[164:167], v[196:199], v[40:43]
	v_mfma_f32_16x16x32_bf16 v[28:31], v[148:151], v[210:213], v[28:31]
	v_mfma_f32_16x16x32_bf16 v[24:27], v[164:167], v[210:213], v[24:27]
	v_mfma_f32_16x16x32_bf16 v[12:15], v[148:151], v[218:221], v[12:15]
	v_mfma_f32_16x16x32_bf16 v[8:11], v[164:167], v[218:221], v[8:11]
	v_mfma_f32_16x16x32_bf16 v[60:63], v[160:163], v[192:195], v[60:63]
	v_mfma_f32_16x16x32_bf16 v[56:59], v[168:171], v[192:195], v[56:59]
	v_mfma_f32_16x16x32_bf16 v[44:47], v[160:163], v[200:203], v[44:47]
	v_mfma_f32_16x16x32_bf16 v[40:43], v[168:171], v[200:203], v[40:43]
	v_mfma_f32_16x16x32_bf16 v[28:31], v[160:163], v[214:217], v[28:31]
	v_mfma_f32_16x16x32_bf16 v[24:27], v[168:171], v[214:217], v[24:27]
	v_mfma_f32_16x16x32_bf16 v[12:15], v[160:163], v[222:225], v[12:15]
	v_mfma_f32_16x16x32_bf16 v[8:11], v[168:171], v[222:225], v[8:11]
	s_setprio 0
	s_setprio 3
	v_mfma_f32_16x16x32_bf16 v[52:55], v[172:175], v[188:191], v[52:55]
	v_mfma_f32_16x16x32_bf16 v[48:51], v[180:183], v[188:191], v[48:51]
	v_mfma_f32_16x16x32_bf16 v[36:39], v[172:175], v[196:199], v[36:39]
	v_mfma_f32_16x16x32_bf16 v[32:35], v[180:183], v[196:199], v[32:35]
	v_mfma_f32_16x16x32_bf16 v[20:23], v[172:175], v[210:213], v[20:23]
	v_mfma_f32_16x16x32_bf16 v[16:19], v[180:183], v[210:213], v[16:19]
	v_mfma_f32_16x16x32_bf16 v[4:7], v[172:175], v[218:221], v[4:7]
	v_mfma_f32_16x16x32_bf16 v[0:3], v[180:183], v[218:221], v[0:3]
	v_mfma_f32_16x16x32_bf16 v[52:55], v[176:179], v[192:195], v[52:55]
	v_mfma_f32_16x16x32_bf16 v[48:51], v[184:187], v[192:195], v[48:51]
	v_mfma_f32_16x16x32_bf16 v[36:39], v[176:179], v[200:203], v[36:39]
	v_mfma_f32_16x16x32_bf16 v[32:35], v[184:187], v[200:203], v[32:35]
	v_mfma_f32_16x16x32_bf16 v[20:23], v[176:179], v[214:217], v[20:23]
	v_mfma_f32_16x16x32_bf16 v[16:19], v[184:187], v[214:217], v[16:19]
	v_mfma_f32_16x16x32_bf16 v[4:7], v[176:179], v[222:225], v[4:7]
	v_mfma_f32_16x16x32_bf16 v[0:3], v[184:187], v[222:225], v[0:3]
	s_barrier
	s_setprio 0
	s_add_i32 s65, 0, 0x18000
	s_add_i32 s66, 0, 0x1c000
	ds_read_b128 v[148:151], v234
	ds_read_b128 v[160:163], v234 offset:1024
	ds_read_b128 v[164:167], v234 offset:2048
	ds_read_b128 v[168:171], v234 offset:3072
	ds_read_b128 v[172:175], v235
	ds_read_b128 v[176:179], v235 offset:1024
	ds_read_b128 v[180:183], v235 offset:2048
	ds_read_b128 v[184:187], v235 offset:3072
	s_add_u32 s0, s40, 0x100000
	s_addc_u32 s1, s41, 0
	s_mov_b32 m0, s44
	ds_read_b128 v[188:191], v158 offset:32768
	ds_read_b128 v[192:195], v158 offset:33792
	ds_read_b128 v[196:199], v158 offset:34816
	ds_read_b128 v[200:203], v158 offset:35840
	ds_read_b128 v[210:213], v158 offset:36864
	ds_read_b128 v[214:217], v158 offset:37888
	ds_read_b128 v[218:221], v158 offset:38912
	global_load_lds_dwordx4 v130, s[0:1]
	s_mov_b32 m0, s45
	ds_read_b128 v[222:225], v158 offset:39936
	global_load_lds_dwordx4 v134, s[0:1]
	s_waitcnt vmcnt(8)
	s_waitcnt lgkmcnt(0)
	s_setprio 3
	s_barrier
	v_mfma_f32_16x16x32_bf16 v[124:127], v[148:151], v[188:191], v[124:127]
	v_mfma_f32_16x16x32_bf16 v[120:123], v[164:167], v[188:191], v[120:123]
	v_mfma_f32_16x16x32_bf16 v[108:111], v[148:151], v[196:199], v[108:111]
	v_mfma_f32_16x16x32_bf16 v[104:107], v[164:167], v[196:199], v[104:107]
	v_mfma_f32_16x16x32_bf16 v[92:95], v[148:151], v[210:213], v[92:95]
	v_mfma_f32_16x16x32_bf16 v[88:91], v[164:167], v[210:213], v[88:91]
	v_mfma_f32_16x16x32_bf16 v[76:79], v[148:151], v[218:221], v[76:79]
	v_mfma_f32_16x16x32_bf16 v[72:75], v[164:167], v[218:221], v[72:75]
	v_mfma_f32_16x16x32_bf16 v[124:127], v[160:163], v[192:195], v[124:127]
	v_mfma_f32_16x16x32_bf16 v[120:123], v[168:171], v[192:195], v[120:123]
	v_mfma_f32_16x16x32_bf16 v[108:111], v[160:163], v[200:203], v[108:111]
	v_mfma_f32_16x16x32_bf16 v[104:107], v[168:171], v[200:203], v[104:107]
	v_mfma_f32_16x16x32_bf16 v[92:95], v[160:163], v[214:217], v[92:95]
	v_mfma_f32_16x16x32_bf16 v[88:91], v[168:171], v[214:217], v[88:91]
	v_mfma_f32_16x16x32_bf16 v[76:79], v[160:163], v[222:225], v[76:79]
	v_mfma_f32_16x16x32_bf16 v[72:75], v[168:171], v[222:225], v[72:75]
	s_setprio 0
	s_setprio 3
	v_mfma_f32_16x16x32_bf16 v[116:119], v[172:175], v[188:191], v[116:119]
	v_mfma_f32_16x16x32_bf16 v[112:115], v[180:183], v[188:191], v[112:115]
	v_mfma_f32_16x16x32_bf16 v[100:103], v[172:175], v[196:199], v[100:103]
	v_mfma_f32_16x16x32_bf16 v[96:99], v[180:183], v[196:199], v[96:99]
	v_mfma_f32_16x16x32_bf16 v[84:87], v[172:175], v[210:213], v[84:87]
	v_mfma_f32_16x16x32_bf16 v[80:83], v[180:183], v[210:213], v[80:83]
	v_mfma_f32_16x16x32_bf16 v[68:71], v[172:175], v[218:221], v[68:71]
	v_mfma_f32_16x16x32_bf16 v[64:67], v[180:183], v[218:221], v[64:67]
	v_mfma_f32_16x16x32_bf16 v[116:119], v[176:179], v[192:195], v[116:119]
	v_mfma_f32_16x16x32_bf16 v[112:115], v[184:187], v[192:195], v[112:115]
	v_mfma_f32_16x16x32_bf16 v[100:103], v[176:179], v[200:203], v[100:103]
	v_mfma_f32_16x16x32_bf16 v[96:99], v[184:187], v[200:203], v[96:99]
	v_mfma_f32_16x16x32_bf16 v[84:87], v[176:179], v[214:217], v[84:87]
	v_mfma_f32_16x16x32_bf16 v[80:83], v[184:187], v[214:217], v[80:83]
	v_mfma_f32_16x16x32_bf16 v[68:71], v[176:179], v[222:225], v[68:71]
	v_mfma_f32_16x16x32_bf16 v[64:67], v[184:187], v[222:225], v[64:67]
	s_barrier
	s_setprio 0
	s_add_i32 s0, s65, s43
	s_add_u32 s100, s38, 0x80
	s_addc_u32 s101, s39, 0
	s_mov_b32 m0, s0
	ds_read_b128 v[188:191], v158 offset:49152
	ds_read_b128 v[192:195], v158 offset:50176
	ds_read_b128 v[196:199], v158 offset:51200
	ds_read_b128 v[200:203], v158 offset:52224
	global_load_lds_dwordx4 v132, s[100:101]
	s_add_i32 m0, s0, 0x2000
	s_add_u32 s100, s38, 0x80
	s_addc_u32 s101, s39, 0
	s_add_u32 s0, s38, 0x100080
	s_addc_u32 s1, s39, 0
	s_add_i32 s38, s66, s43
	global_load_lds_dwordx4 v136, s[100:101]
	s_mov_b32 m0, s38
	ds_read_b128 v[222:225], v158 offset:56320
	global_load_lds_dwordx4 v132, s[0:1]
	s_add_i32 m0, s38, 0x2000
	ds_read_b128 v[218:221], v158 offset:55296
	global_load_lds_dwordx4 v136, s[0:1]
	s_add_u32 s100, s40, 0x80
	s_addc_u32 s101, s41, 0
	s_mov_b32 m0, s49
	ds_read_b128 v[214:217], v158 offset:54272
	global_load_lds_dwordx4 v130, s[100:101]
	s_add_u32 s100, s40, 0x80
	s_addc_u32 s101, s41, 0
	s_mov_b32 m0, s50
	ds_read_b128 v[210:213], v158 offset:53248
	global_load_lds_dwordx4 v134, s[100:101]
	s_waitcnt vmcnt(8)
	s_waitcnt lgkmcnt(0)
	s_setprio 3
	s_barrier
	v_mfma_f32_16x16x32_bf16 v[60:63], v[148:151], v[188:191], v[60:63]
	v_mfma_f32_16x16x32_bf16 v[56:59], v[164:167], v[188:191], v[56:59]
	v_mfma_f32_16x16x32_bf16 v[44:47], v[148:151], v[196:199], v[44:47]
	v_mfma_f32_16x16x32_bf16 v[40:43], v[164:167], v[196:199], v[40:43]
	v_mfma_f32_16x16x32_bf16 v[28:31], v[148:151], v[210:213], v[28:31]
	v_mfma_f32_16x16x32_bf16 v[24:27], v[164:167], v[210:213], v[24:27]
	v_mfma_f32_16x16x32_bf16 v[12:15], v[148:151], v[218:221], v[12:15]
	v_mfma_f32_16x16x32_bf16 v[8:11], v[164:167], v[218:221], v[8:11]
	v_mfma_f32_16x16x32_bf16 v[60:63], v[160:163], v[192:195], v[60:63]
	v_mfma_f32_16x16x32_bf16 v[56:59], v[168:171], v[192:195], v[56:59]
	v_mfma_f32_16x16x32_bf16 v[44:47], v[160:163], v[200:203], v[44:47]
	v_mfma_f32_16x16x32_bf16 v[40:43], v[168:171], v[200:203], v[40:43]
	v_mfma_f32_16x16x32_bf16 v[28:31], v[160:163], v[214:217], v[28:31]
	v_mfma_f32_16x16x32_bf16 v[24:27], v[168:171], v[214:217], v[24:27]
	v_mfma_f32_16x16x32_bf16 v[12:15], v[160:163], v[222:225], v[12:15]
	v_mfma_f32_16x16x32_bf16 v[8:11], v[168:171], v[222:225], v[8:11]
	s_setprio 0
	s_setprio 3
	v_mfma_f32_16x16x32_bf16 v[52:55], v[172:175], v[188:191], v[52:55]
	v_mfma_f32_16x16x32_bf16 v[48:51], v[180:183], v[188:191], v[48:51]
	v_mfma_f32_16x16x32_bf16 v[36:39], v[172:175], v[196:199], v[36:39]
	v_mfma_f32_16x16x32_bf16 v[32:35], v[180:183], v[196:199], v[32:35]
	v_mfma_f32_16x16x32_bf16 v[20:23], v[172:175], v[210:213], v[20:23]
	v_mfma_f32_16x16x32_bf16 v[16:19], v[180:183], v[210:213], v[16:19]
	v_mfma_f32_16x16x32_bf16 v[4:7], v[172:175], v[218:221], v[4:7]
	v_mfma_f32_16x16x32_bf16 v[0:3], v[180:183], v[218:221], v[0:3]
	v_mfma_f32_16x16x32_bf16 v[52:55], v[176:179], v[192:195], v[52:55]
	v_mfma_f32_16x16x32_bf16 v[48:51], v[184:187], v[192:195], v[48:51]
	v_mfma_f32_16x16x32_bf16 v[36:39], v[176:179], v[200:203], v[36:39]
	v_mfma_f32_16x16x32_bf16 v[32:35], v[184:187], v[200:203], v[32:35]
	v_mfma_f32_16x16x32_bf16 v[20:23], v[176:179], v[214:217], v[20:23]
	v_mfma_f32_16x16x32_bf16 v[16:19], v[184:187], v[214:217], v[16:19]
	v_mfma_f32_16x16x32_bf16 v[4:7], v[176:179], v[222:225], v[4:7]
	v_mfma_f32_16x16x32_bf16 v[0:3], v[184:187], v[222:225], v[0:3]
	s_barrier
	s_setprio 0
	s_add_u32 s36, s36, 0x100
	s_addc_u32 s37, s37, 0
	s_add_i32 s64, s64, 2
	s_add_u32 s62, s62, 0x100
	s_addc_u32 s63, s63, 0
	s_cmp_gt_u32 s64, 61
	s_cbranch_scc0 .LBB0_1813
	s_and_b64 vcc, exec, s[14:15]
	s_cbranch_vccz .LBB0_1816
	s_barrier

.LBB0_1832:
	s_ashr_i32 s19, s18, 31
	s_lshl_b64 s[0:1], s[18:19], 20
	s_add_u32 s20, s25, s0
	s_addc_u32 s21, s42, s1
	s_and_b64 s[0:1], s[6:7], exec
	s_cselect_b32 s26, s21, s37
	s_cselect_b32 s27, s20, s36
	s_ashr_i32 s17, s16, 31
	s_lshl_b64 s[0:1], s[16:17], 20
	s_add_u32 s28, s43, s0
	s_addc_u32 s29, s44, s1
	s_and_b64 s[0:1], s[6:7], exec
	s_cselect_b32 s17, s29, s39
	s_cselect_b32 s31, s28, s38
	s_add_u32 s36, s36, 0x80080
	s_addc_u32 s37, s37, 0
	s_add_u32 s63, s38, 0x100
	v_mov_b32_e32 v32, 0
	s_addc_u32 s64, s39, 0
	s_mov_b32 s65, -2
	v_mov_b64_e32 v[32:33], 0
	v_mov_b64_e32 v[34:35], 0
	v_mov_b64_e32 v[36:37], 0
	v_mov_b64_e32 v[38:39], 0
	v_mov_b64_e32 v[40:41], 0
	v_mov_b64_e32 v[42:43], 0
	v_mov_b64_e32 v[44:45], 0
	v_mov_b64_e32 v[46:47], 0
	v_mov_b64_e32 v[48:49], 0
	v_mov_b64_e32 v[50:51], 0
	v_mov_b64_e32 v[52:53], 0
	v_mov_b64_e32 v[54:55], 0
	v_mov_b64_e32 v[56:57], 0
	v_mov_b64_e32 v[58:59], 0
	v_mov_b64_e32 v[60:61], 0
	v_mov_b64_e32 v[62:63], 0
	v_mov_b64_e32 v[64:65], 0
	v_mov_b64_e32 v[66:67], 0
	v_mov_b64_e32 v[68:69], 0
	v_mov_b64_e32 v[70:71], 0
	v_mov_b64_e32 v[72:73], 0
	v_mov_b64_e32 v[74:75], 0
	v_mov_b64_e32 v[76:77], 0
	v_mov_b64_e32 v[78:79], 0
	v_mov_b64_e32 v[80:81], 0
	v_mov_b64_e32 v[82:83], 0
	v_mov_b64_e32 v[84:85], 0
	v_mov_b64_e32 v[86:87], 0
	v_mov_b64_e32 v[88:89], 0
	v_mov_b64_e32 v[90:91], 0
	v_mov_b64_e32 v[92:93], 0
	v_mov_b64_e32 v[94:95], 0
	v_mov_b64_e32 v[96:97], 0
	v_mov_b64_e32 v[98:99], 0
	v_mov_b64_e32 v[100:101], 0
	v_mov_b64_e32 v[102:103], 0
	v_mov_b64_e32 v[104:105], 0
	v_mov_b64_e32 v[106:107], 0
	v_mov_b64_e32 v[108:109], 0
	v_mov_b64_e32 v[110:111], 0
	v_mov_b64_e32 v[112:113], 0
	v_mov_b64_e32 v[114:115], 0
	v_mov_b64_e32 v[116:117], 0
	v_mov_b64_e32 v[118:119], 0
	v_mov_b64_e32 v[120:121], 0
	v_mov_b64_e32 v[122:123], 0
	v_mov_b64_e32 v[124:125], 0
	v_mov_b64_e32 v[126:127], 0
	v_mov_b64_e32 v[128:129], 0
	v_mov_b64_e32 v[130:131], 0
	v_mov_b64_e32 v[132:133], 0
	v_mov_b64_e32 v[134:135], 0
	v_mov_b64_e32 v[136:137], 0
	v_mov_b64_e32 v[138:139], 0
	v_mov_b64_e32 v[140:141], 0
	v_mov_b64_e32 v[142:143], 0
	v_mov_b64_e32 v[144:145], 0
	v_mov_b64_e32 v[146:147], 0
	v_mov_b64_e32 v[148:149], 0
	v_mov_b64_e32 v[150:151], 0
	v_mov_b64_e32 v[152:153], 0
	v_mov_b64_e32 v[154:155], 0
	v_mov_b64_e32 v[156:157], 0
	v_mov_b64_e32 v[158:159], 0
	v_add_u32_e32 v198, 0x18000, v190
	v_add_u32_e32 v199, 0x1c000, v190
.LBB0_1833:
	ds_read_b128 v[24:27], v193
	ds_read_b128 v[28:31], v193 offset:1024
	ds_read_b128 v[16:19], v193 offset:2048
	ds_read_b128 v[20:23], v193 offset:3072
	ds_read_b128 v[8:11], v194
	ds_read_b128 v[12:15], v194 offset:1024
	ds_read_b128 v[0:3], v194 offset:2048
	ds_read_b128 v[4:7], v194 offset:3072
	s_add_u32 s0, s36, 0xfff80080
	s_addc_u32 s1, s37, -1
	s_cmp_eq_u32 s65, 28
	s_cselect_b32 s41, s26, s1
	s_cselect_b32 s40, s27, s0
	s_cselect_b32 s39, s17, s64
	s_cselect_b32 s38, s31, s63
	s_add_i32 m0, s35, 0xc000
	ds_read_b128 v[180:183], v195
	ds_read_b128 v[184:187], v195 offset:1024
	ds_read_b128 v[210:213], v195 offset:2048
	ds_read_b128 v[214:217], v195 offset:3072
	ds_read_b128 v[218:221], v195 offset:4096
	ds_read_b128 v[222:225], v195 offset:5120
	ds_read_b128 v[226:229], v195 offset:6144
	global_load_lds_dwordx4 v172, s[36:37]
	s_add_i32 m0, s35, 0xe000
	ds_read_b128 v[230:233], v195 offset:7168
	global_load_lds_dwordx4 v174, s[36:37]
	s_waitcnt vmcnt(8)
	s_waitcnt lgkmcnt(0)
	s_setprio 3
	s_barrier
	v_mfma_scale_f32_16x16x128_f8f6f4 v[152:155], v[24:31], v[180:187], v[152:155], v188, v188 op_sel_hi:[0,0,0]
	v_mfma_scale_f32_16x16x128_f8f6f4 v[148:151], v[16:23], v[180:187], v[148:151], v188, v188 op_sel_hi:[0,0,0]
	v_mfma_scale_f32_16x16x128_f8f6f4 v[140:143], v[24:31], v[210:217], v[140:143], v188, v188 op_sel_hi:[0,0,0]
	v_mfma_scale_f32_16x16x128_f8f6f4 v[132:135], v[16:23], v[210:217], v[132:135], v188, v188 op_sel_hi:[0,0,0]
	v_mfma_scale_f32_16x16x128_f8f6f4 v[124:127], v[24:31], v[218:225], v[124:127], v188, v188 op_sel_hi:[0,0,0]
	v_mfma_scale_f32_16x16x128_f8f6f4 v[120:123], v[16:23], v[218:225], v[120:123], v188, v188 op_sel_hi:[0,0,0]
	v_mfma_scale_f32_16x16x128_f8f6f4 v[108:111], v[24:31], v[226:233], v[108:111], v188, v188 op_sel_hi:[0,0,0]
	v_mfma_scale_f32_16x16x128_f8f6f4 v[100:103], v[16:23], v[226:233], v[100:103], v188, v188 op_sel_hi:[0,0,0]
	s_setprio 0
	s_setprio 3
	v_mfma_scale_f32_16x16x128_f8f6f4 v[156:159], v[8:15], v[180:187], v[156:159], v188, v188 op_sel_hi:[0,0,0]
	v_mfma_scale_f32_16x16x128_f8f6f4 v[144:147], v[0:7], v[180:187], v[144:147], v188, v188 op_sel_hi:[0,0,0]
	v_mfma_scale_f32_16x16x128_f8f6f4 v[136:139], v[8:15], v[210:217], v[136:139], v188, v188 op_sel_hi:[0,0,0]
	v_mfma_scale_f32_16x16x128_f8f6f4 v[128:131], v[0:7], v[210:217], v[128:131], v188, v188 op_sel_hi:[0,0,0]
	v_mfma_scale_f32_16x16x128_f8f6f4 v[116:119], v[8:15], v[218:225], v[116:119], v188, v188 op_sel_hi:[0,0,0]
	v_mfma_scale_f32_16x16x128_f8f6f4 v[112:115], v[0:7], v[218:225], v[112:115], v188, v188 op_sel_hi:[0,0,0]
	v_mfma_scale_f32_16x16x128_f8f6f4 v[104:107], v[8:15], v[226:233], v[104:107], v188, v188 op_sel_hi:[0,0,0]
	v_mfma_scale_f32_16x16x128_f8f6f4 v[96:99], v[0:7], v[226:233], v[96:99], v188, v188 op_sel_hi:[0,0,0]
	s_barrier
	s_setprio 0
	s_add_i32 s0, s56, s45
	s_mov_b32 m0, s0
	ds_read_b128 v[210:213], v195 offset:16384
	ds_read_b128 v[214:217], v195 offset:17408
	ds_read_b128 v[218:221], v195 offset:18432
	ds_read_b128 v[222:225], v195 offset:19456
	ds_read_b128 v[226:229], v195 offset:20480
	global_load_lds_dwordx4 v164, s[38:39]
	s_add_i32 m0, s0, 0x2000
	s_add_u32 s0, s38, 0x80000
	s_addc_u32 s1, s39, 0
	s_add_i32 s66, s57, s45
	global_load_lds_dwordx4 v168, s[38:39]
	s_mov_b32 m0, s66
	s_nop 0
	global_load_lds_dwordx4 v164, s[0:1]
	s_add_i32 m0, s66, 0x2000
	ds_read_b128 v[238:241], v195 offset:23552
	global_load_lds_dwordx4 v168, s[0:1]
	s_mov_b32 m0, s35
	ds_read_b128 v[234:237], v195 offset:22528
	global_load_lds_dwordx4 v162, s[40:41]
	s_mov_b32 m0, s46
	ds_read_b128 v[230:233], v195 offset:21504
	global_load_lds_dwordx4 v166, s[40:41]
	s_waitcnt vmcnt(8)
	s_waitcnt lgkmcnt(0)
	s_setprio 3
	s_barrier
	v_mfma_scale_f32_16x16x128_f8f6f4 v[92:95], v[24:31], v[210:217], v[92:95], v188, v188 op_sel_hi:[0,0,0]
	v_mfma_scale_f32_16x16x128_f8f6f4 v[88:91], v[16:23], v[210:217], v[88:91], v188, v188 op_sel_hi:[0,0,0]
	v_mfma_scale_f32_16x16x128_f8f6f4 v[76:79], v[24:31], v[218:225], v[76:79], v188, v188 op_sel_hi:[0,0,0]
	v_mfma_scale_f32_16x16x128_f8f6f4 v[68:71], v[16:23], v[218:225], v[68:71], v188, v188 op_sel_hi:[0,0,0]
	v_mfma_scale_f32_16x16x128_f8f6f4 v[60:63], v[24:31], v[226:233], v[60:63], v188, v188 op_sel_hi:[0,0,0]
	v_mfma_scale_f32_16x16x128_f8f6f4 v[56:59], v[16:23], v[226:233], v[56:59], v188, v188 op_sel_hi:[0,0,0]
	v_mfma_scale_f32_16x16x128_f8f6f4 v[44:47], v[24:31], v[234:241], v[44:47], v188, v188 op_sel_hi:[0,0,0]
	v_mfma_scale_f32_16x16x128_f8f6f4 v[40:43], v[16:23], v[234:241], v[40:43], v188, v188 op_sel_hi:[0,0,0]
	s_setprio 0
	s_setprio 3
	v_mfma_scale_f32_16x16x128_f8f6f4 v[84:87], v[8:15], v[210:217], v[84:87], v188, v188 op_sel_hi:[0,0,0]
	v_mfma_scale_f32_16x16x128_f8f6f4 v[80:83], v[0:7], v[210:217], v[80:83], v188, v188 op_sel_hi:[0,0,0]
	v_mfma_scale_f32_16x16x128_f8f6f4 v[72:75], v[8:15], v[218:225], v[72:75], v188, v188 op_sel_hi:[0,0,0]
	v_mfma_scale_f32_16x16x128_f8f6f4 v[64:67], v[0:7], v[218:225], v[64:67], v188, v188 op_sel_hi:[0,0,0]
	v_mfma_scale_f32_16x16x128_f8f6f4 v[52:55], v[8:15], v[226:233], v[52:55], v188, v188 op_sel_hi:[0,0,0]
	v_mfma_scale_f32_16x16x128_f8f6f4 v[48:51], v[0:7], v[226:233], v[48:51], v188, v188 op_sel_hi:[0,0,0]
	v_mfma_scale_f32_16x16x128_f8f6f4 v[36:39], v[8:15], v[234:241], v[36:39], v188, v188 op_sel_hi:[0,0,0]
	v_mfma_scale_f32_16x16x128_f8f6f4 v[32:35], v[0:7], v[234:241], v[32:35], v188, v188 op_sel_hi:[0,0,0]
	s_barrier
	s_setprio 0
	s_add_i32 s66, 0, 0x18000
	s_add_i32 s67, 0, 0x1c000
	ds_read_b128 v[0:3], v198
	ds_read_b128 v[4:7], v198 offset:1024
	ds_read_b128 v[8:11], v198 offset:2048
	ds_read_b128 v[12:15], v198 offset:3072
	ds_read_b128 v[16:19], v199
	ds_read_b128 v[20:23], v199 offset:1024
	ds_read_b128 v[24:27], v199 offset:2048
	ds_read_b128 v[28:31], v199 offset:3072
	s_add_u32 s0, s40, 0x80000
	s_addc_u32 s1, s41, 0
	s_mov_b32 m0, s47
	ds_read_b128 v[210:213], v195 offset:32768
	ds_read_b128 v[214:217], v195 offset:33792
	ds_read_b128 v[218:221], v195 offset:34816
	ds_read_b128 v[222:225], v195 offset:35840
	ds_read_b128 v[226:229], v195 offset:36864
	ds_read_b128 v[230:233], v195 offset:37888
	ds_read_b128 v[234:237], v195 offset:38912
	global_load_lds_dwordx4 v162, s[0:1]
	s_mov_b32 m0, s48
	ds_read_b128 v[238:241], v195 offset:39936
	global_load_lds_dwordx4 v166, s[0:1]
	s_waitcnt vmcnt(8)
	s_waitcnt lgkmcnt(0)
	s_setprio 3
	s_barrier
	v_mfma_scale_f32_16x16x128_f8f6f4 v[152:155], v[0:7], v[210:217], v[152:155], v188, v188 op_sel_hi:[0,0,0]
	v_mfma_scale_f32_16x16x128_f8f6f4 v[148:151], v[8:15], v[210:217], v[148:151], v188, v188 op_sel_hi:[0,0,0]
	v_mfma_scale_f32_16x16x128_f8f6f4 v[140:143], v[0:7], v[218:225], v[140:143], v188, v188 op_sel_hi:[0,0,0]
	v_mfma_scale_f32_16x16x128_f8f6f4 v[132:135], v[8:15], v[218:225], v[132:135], v188, v188 op_sel_hi:[0,0,0]
	v_mfma_scale_f32_16x16x128_f8f6f4 v[124:127], v[0:7], v[226:233], v[124:127], v188, v188 op_sel_hi:[0,0,0]
	v_mfma_scale_f32_16x16x128_f8f6f4 v[120:123], v[8:15], v[226:233], v[120:123], v188, v188 op_sel_hi:[0,0,0]
	v_mfma_scale_f32_16x16x128_f8f6f4 v[108:111], v[0:7], v[234:241], v[108:111], v188, v188 op_sel_hi:[0,0,0]
	v_mfma_scale_f32_16x16x128_f8f6f4 v[100:103], v[8:15], v[234:241], v[100:103], v188, v188 op_sel_hi:[0,0,0]
	s_setprio 0
	s_setprio 3
	v_mfma_scale_f32_16x16x128_f8f6f4 v[156:159], v[16:23], v[210:217], v[156:159], v188, v188 op_sel_hi:[0,0,0]
	v_mfma_scale_f32_16x16x128_f8f6f4 v[144:147], v[24:31], v[210:217], v[144:147], v188, v188 op_sel_hi:[0,0,0]
	v_mfma_scale_f32_16x16x128_f8f6f4 v[136:139], v[16:23], v[218:225], v[136:139], v188, v188 op_sel_hi:[0,0,0]
	v_mfma_scale_f32_16x16x128_f8f6f4 v[128:131], v[24:31], v[218:225], v[128:131], v188, v188 op_sel_hi:[0,0,0]
	v_mfma_scale_f32_16x16x128_f8f6f4 v[116:119], v[16:23], v[226:233], v[116:119], v188, v188 op_sel_hi:[0,0,0]
	v_mfma_scale_f32_16x16x128_f8f6f4 v[112:115], v[24:31], v[226:233], v[112:115], v188, v188 op_sel_hi:[0,0,0]
	v_mfma_scale_f32_16x16x128_f8f6f4 v[104:107], v[16:23], v[234:241], v[104:107], v188, v188 op_sel_hi:[0,0,0]
	v_mfma_scale_f32_16x16x128_f8f6f4 v[96:99], v[24:31], v[234:241], v[96:99], v188, v188 op_sel_hi:[0,0,0]
	s_barrier
	s_setprio 0
	s_add_i32 s0, s66, s45
	s_add_u32 s100, s38, 0x80
	s_addc_u32 s101, s39, 0
	s_mov_b32 m0, s0
	ds_read_b128 v[210:213], v195 offset:49152
	ds_read_b128 v[214:217], v195 offset:50176
	ds_read_b128 v[218:221], v195 offset:51200
	ds_read_b128 v[222:225], v195 offset:52224
	global_load_lds_dwordx4 v164, s[100:101]
	s_add_i32 m0, s0, 0x2000
	s_add_u32 s100, s38, 0x80
	s_addc_u32 s101, s39, 0
	s_add_u32 s0, s38, 0x80080
	s_addc_u32 s1, s39, 0
	s_add_i32 s38, s67, s45
	global_load_lds_dwordx4 v168, s[100:101]
	s_mov_b32 m0, s38
	ds_read_b128 v[238:241], v195 offset:56320
	global_load_lds_dwordx4 v164, s[0:1]
	s_add_i32 m0, s38, 0x2000
	ds_read_b128 v[234:237], v195 offset:55296
	global_load_lds_dwordx4 v168, s[0:1]
	s_add_u32 s100, s40, 0x80
	s_addc_u32 s101, s41, 0
	s_mov_b32 m0, s51
	ds_read_b128 v[230:233], v195 offset:54272
	global_load_lds_dwordx4 v162, s[100:101]
	s_add_u32 s100, s40, 0x80
	s_addc_u32 s101, s41, 0
	s_mov_b32 m0, s52
	ds_read_b128 v[226:229], v195 offset:53248
	global_load_lds_dwordx4 v166, s[100:101]
	s_waitcnt vmcnt(8)
	s_waitcnt lgkmcnt(0)
	s_setprio 3
	s_barrier
	v_mfma_scale_f32_16x16x128_f8f6f4 v[92:95], v[0:7], v[210:217], v[92:95], v188, v188 op_sel_hi:[0,0,0]
	v_mfma_scale_f32_16x16x128_f8f6f4 v[88:91], v[8:15], v[210:217], v[88:91], v188, v188 op_sel_hi:[0,0,0]
	v_mfma_scale_f32_16x16x128_f8f6f4 v[76:79], v[0:7], v[218:225], v[76:79], v188, v188 op_sel_hi:[0,0,0]
	v_mfma_scale_f32_16x16x128_f8f6f4 v[68:71], v[8:15], v[218:225], v[68:71], v188, v188 op_sel_hi:[0,0,0]
	v_mfma_scale_f32_16x16x128_f8f6f4 v[60:63], v[0:7], v[226:233], v[60:63], v188, v188 op_sel_hi:[0,0,0]
	v_mfma_scale_f32_16x16x128_f8f6f4 v[56:59], v[8:15], v[226:233], v[56:59], v188, v188 op_sel_hi:[0,0,0]
	v_mfma_scale_f32_16x16x128_f8f6f4 v[44:47], v[0:7], v[234:241], v[44:47], v188, v188 op_sel_hi:[0,0,0]
	v_mfma_scale_f32_16x16x128_f8f6f4 v[40:43], v[8:15], v[234:241], v[40:43], v188, v188 op_sel_hi:[0,0,0]
	s_setprio 0
	s_setprio 3
	v_mfma_scale_f32_16x16x128_f8f6f4 v[84:87], v[16:23], v[210:217], v[84:87], v188, v188 op_sel_hi:[0,0,0]
	v_mfma_scale_f32_16x16x128_f8f6f4 v[80:83], v[24:31], v[210:217], v[80:83], v188, v188 op_sel_hi:[0,0,0]
	v_mfma_scale_f32_16x16x128_f8f6f4 v[72:75], v[16:23], v[218:225], v[72:75], v188, v188 op_sel_hi:[0,0,0]
	v_mfma_scale_f32_16x16x128_f8f6f4 v[64:67], v[24:31], v[218:225], v[64:67], v188, v188 op_sel_hi:[0,0,0]
	v_mfma_scale_f32_16x16x128_f8f6f4 v[52:55], v[16:23], v[226:233], v[52:55], v188, v188 op_sel_hi:[0,0,0]
	v_mfma_scale_f32_16x16x128_f8f6f4 v[48:51], v[24:31], v[226:233], v[48:51], v188, v188 op_sel_hi:[0,0,0]
	v_mfma_scale_f32_16x16x128_f8f6f4 v[36:39], v[16:23], v[234:241], v[36:39], v188, v188 op_sel_hi:[0,0,0]
	v_mfma_scale_f32_16x16x128_f8f6f4 v[32:35], v[24:31], v[234:241], v[32:35], v188, v188 op_sel_hi:[0,0,0]
	s_barrier
	s_setprio 0
	s_add_u32 s36, s36, 0x100
	s_addc_u32 s37, s37, 0
	s_add_i32 s65, s65, 2
	s_add_u32 s63, s63, 0x100
	s_addc_u32 s64, s64, 0
	s_cmp_gt_u32 s65, 29
	s_cbranch_scc0 .LBB0_1833
	s_and_b64 vcc, exec, s[14:15]
	s_cbranch_vccz .LBB0_1836
	s_barrier
